# epilogue sumsq loads hoisted with counted vmcnt waits in gate-up, kv-up, q-up GEMM epilogues; SSM nop chains trimmed; MLA change reverted
# speedup vs baseline: 1.0121x; 1.0121x over previous
; DI float ss_get(const ssacc_t* p) { const ssacc_t v = *p; return (float)(unsigned)(v >> 32) + (float)(unsigned)(v & 0xffffffffull) * 2.3283064365386963e-10f; }
; DI u32x4 pack8(const f32x4& a, const f32x4& b) { u32x4 w; w.x = cvtpk(a[0], a[1]); w.y = cvtpk(a[2], a[3]); w.z = cvtpk(b[0], b[1]); w.w = cvtpk(b[2], b[3]); return w; }
;     DI const bf16_t* Q() const { return (const bf16_t*)(ws + WS_Q); }
;     DI void operator()(const Acc& acc, const Unit& u, int wr, int wc, int fr, int fq) const {
; #pragma unroll
;         for (int ai = 0; ai < 2; ++ai)
; #pragma unroll
;             for (int m = 0; m < 4; ++m) {
;                 asm volatile("" ::: "memory");
;                 const int row = u.pm * 256 + ai * 128 + wr * 64 + m * 16 + fr;
;                 const float rs = rsqrtf(ss_get(ssq + row) * (1.f / 512.f) + EPS_) * QSCALE_MLA;
; #pragma unroll
;                 for (int bj = 0; bj < 2; ++bj) {
;                     f32x4 v0 = acc[ai][bj][m][0] * rs, v1 = acc[ai][bj][m][1] * rs;
;                     const int c0 = u.pn * 256 + bj * 128 + wc * 32 + 8 * fq;
;                     const int w = c0 % 192;
;                     if (w >= 128) rope8(v0, v1, rope, row & 2047, (w - 128) >> 1);
;                     *(u32x4*)(Q + (size_t)row * 1536 + c0) = pack8(v0, v1);
;                 }
;             }
;     }
.LBB0_808:
	v_lshl_add_u32 v144, s49, 8, v150
	v_ashrrev_i32_e32 v145, 31, v144
	v_lshl_add_u64 v[146:147], v[144:145], 3, s[44:45]
	global_load_dwordx2 v[212:213], v[146:147], off
	global_load_dwordx2 v[214:215], v[146:147], off offset:128
	global_load_dwordx2 v[216:217], v[146:147], off offset:256
	global_load_dwordx2 v[218:219], v[146:147], off offset:384
	global_load_dwordx2 v[220:221], v[146:147], off offset:1024
	global_load_dwordx2 v[222:223], v[146:147], off offset:1152
	global_load_dwordx2 v[224:225], v[146:147], off offset:1280
	global_load_dwordx2 v[226:227], v[146:147], off offset:1408
	s_min_u32 s14, s88, 32
	s_sub_i32 s15, 32, s14
	v_lshl_or_b32 v142, s48, 8, v152
	s_mov_b32 s4, 0x2aaaaaab
	s_waitcnt vmcnt(7)
	v_mov_b32_e32 v146, v212
	v_mov_b32_e32 v147, v213
	v_mov_b32_e32 v128, v147
	v_lshlrev_b64 v[148:149], s14, v[128:129]
	v_min_u32_e32 v128, 1, v148
	v_or_b32_e32 v128, v149, v128
	v_cvt_f32_u32_e32 v128, v128
	v_cvt_f32_u32_e32 v143, v146
	v_ldexp_f32 v128, v128, s15
	v_fmac_f32_e32 v128, 0x2f800000, v143
	v_fmamk_f32 v128, v128, 0x3b000000, v195
	v_cmp_gt_f32_e32 vcc, s27, v128
	v_mul_f32_e32 v143, 0x4b800000, v128
	s_nop 0
	v_cndmask_b32_e32 v128, v128, v143, vcc
	v_rsq_f32_e32 v128, v128
	s_nop 0
	v_mul_f32_e32 v143, 0x45800000, v128
	v_cndmask_b32_e32 v128, v128, v143, vcc
	v_mul_f32_e32 v146, 0x3dd53b94, v128
	v_pk_mul_f32 v[148:149], v[122:123], v[146:147] op_sel_hi:[1,0]
	v_pk_mul_f32 v[122:123], v[120:121], v[146:147] op_sel_hi:[1,0]
	v_pk_mul_f32 v[120:121], v[124:125], v[146:147] op_sel_hi:[1,0]
	v_mul_hi_i32 v124, v142, s4
	v_lshrrev_b32_e32 v125, 31, v124
	v_lshrrev_b32_e32 v124, 5, v124
	v_add_u32_e32 v124, v124, v125
	s_movk_i32 s4, 0xc0
	v_lshlrev_b32_e32 v128, 8, v144
	v_mul_lo_u32 v124, v124, s4
	v_and_b32_e32 v128, 0x7cf00, v128
	v_sub_u32_e32 v124, v142, v124
	s_movk_i32 s4, 0x7f
	v_add_u32_e32 v128, 0xfffffe00, v128
	v_pk_mul_f32 v[126:127], v[126:127], v[146:147] op_sel_hi:[1,0]
	v_cmp_lt_i32_e32 vcc, s4, v124
	s_and_saveexec_b64 s[6:7], vcc
	s_cbranch_execz .LBB0_810
	v_lshl_add_u32 v125, v124, 2, v128
	global_load_dwordx4 v[154:157], v125, s[50:51] offset:16
	global_load_dwordx4 v[158:161], v125, s[50:51]
	s_waitcnt vmcnt(0)
	v_pk_mul_f32 v[166:167], v[120:121], v[154:155] op_sel:[1,1] op_sel_hi:[0,1]
	v_pk_mul_f32 v[164:165], v[122:123], v[158:159] op_sel:[1,1] op_sel_hi:[0,1]
	v_pk_mul_f32 v[162:163], v[122:123], v[158:159]
	v_pk_fma_f32 v[122:123], v[122:123], v[158:159], v[164:165] op_sel_hi:[1,0,1]
	s_nop 0
	v_mul_f32_e32 v122, v149, v161
	v_pk_fma_f32 v[158:159], v[148:149], v[160:161], v[122:123] op_sel_hi:[1,1,0] neg_lo:[0,0,1] neg_hi:[0,0,1]
	v_mul_f32_e32 v122, v148, v161
	v_pk_fma_f32 v[160:161], v[148:149], v[160:161], v[122:123] op_sel:[1,0,0] op_sel_hi:[0,1,0]
	v_pk_mul_f32 v[148:149], v[120:121], v[154:155]
	v_pk_fma_f32 v[120:121], v[120:121], v[154:155], v[166:167] op_sel_hi:[1,0,1]
	v_sub_f32_e32 v122, v162, v164
	v_mul_f32_e32 v120, v127, v157
	v_pk_fma_f32 v[154:155], v[126:127], v[156:157], v[120:121] op_sel_hi:[1,1,0] neg_lo:[0,0,1] neg_hi:[0,0,1]
	v_mul_f32_e32 v120, v126, v157
	v_pk_fma_f32 v[156:157], v[126:127], v[156:157], v[120:121] op_sel:[1,0,0] op_sel_hi:[0,1,0]
	v_sub_f32_e32 v120, v148, v166
	v_mov_b32_e32 v126, v154
	v_mov_b32_e32 v127, v156
	v_mov_b32_e32 v148, v158
	v_mov_b32_e32 v149, v160

; DI float ss_get(const ssacc_t* p) { const ssacc_t v = *p; return (float)(unsigned)(v >> 32) + (float)(unsigned)(v & 0xffffffffull) * 2.3283064365386963e-10f; }
; DI u32x4 pack8(const f32x4& a, const f32x4& b) { u32x4 w; w.x = cvtpk(a[0], a[1]); w.y = cvtpk(a[2], a[3]); w.z = cvtpk(b[0], b[1]); w.w = cvtpk(b[2], b[3]); return w; }
;     DI const bf16_t* Q() const { return (const bf16_t*)(ws + WS_Q); }
;     DI void operator()(const Acc& acc, const Unit& u, int wr, int wc, int fr, int fq) const {
;     ...
;                 asm volatile("" ::: "memory");
;                 const int row = u.pm * 256 + ai * 128 + wr * 64 + m * 16 + fr;
;                 const float rs = rsqrtf(ss_get(ssq + row) * (1.f / 512.f) + EPS_) * QSCALE_MLA;
; #pragma unroll
;                 for (int bj = 0; bj < 2; ++bj) {
;                     f32x4 v0 = acc[ai][bj][m][0] * rs, v1 = acc[ai][bj][m][1] * rs;
;                     const int c0 = u.pn * 256 + bj * 128 + wc * 32 + 8 * fq;
;                     const int w = c0 % 192;
;                     if (w >= 128) rope8(v0, v1, rope, row & 2047, (w - 128) >> 1);
;                     *(u32x4*)(Q + (size_t)row * 1536 + c0) = pack8(v0, v1);
;                 }
.LBB0_812:
	s_or_b64 exec, exec, s[6:7]
	v_cvt_pk_bf16_f32 v116, v116, v117
	v_cvt_pk_bf16_f32 v117, v118, v119
	v_cvt_pk_bf16_f32 v118, v112, v113
	v_cvt_pk_bf16_f32 v119, v114, v115
	v_or_b32_e32 v112, 16, v144
	global_store_dwordx4 v[120:121], v[116:119], off offset:256
	v_ashrrev_i32_e32 v113, 31, v112
	s_waitcnt vmcnt(8)
	v_mov_b32_e32 v114, v214
	v_mov_b32_e32 v115, v215
	v_mov_b32_e32 v128, v115
	v_lshlrev_b64 v[116:117], s14, v[128:129]
	v_min_u32_e32 v113, 1, v116
	v_or_b32_e32 v113, v117, v113
	v_cvt_f32_u32_e32 v113, v113
	v_cvt_f32_u32_e32 v114, v114
	v_ldexp_f32 v113, v113, s15
	v_fmac_f32_e32 v113, 0x2f800000, v114
	v_fmamk_f32 v113, v113, 0x3b000000, v195
	v_mul_f32_e32 v114, 0x4b800000, v113
	v_cmp_gt_f32_e64 s[6:7], s27, v113
	s_nop 1
	v_cndmask_b32_e64 v113, v113, v114, s[6:7]
	v_rsq_f32_e32 v114, v113
	v_lshlrev_b32_e32 v113, 8, v112
	v_and_b32_e32 v113, 0x7df00, v113
	v_add_u32_e32 v113, 0xfffffe00, v113
	v_mul_f32_e32 v115, 0x45800000, v114
	v_cndmask_b32_e64 v114, v114, v115, s[6:7]
	v_mul_f32_e32 v114, 0x3dd53b94, v114
	v_pk_mul_f32 v[110:111], v[110:111], v[114:115] op_sel_hi:[1,0]
	v_pk_mul_f32 v[108:109], v[108:109], v[114:115] op_sel_hi:[1,0]
	v_pk_mul_f32 v[106:107], v[106:107], v[114:115] op_sel_hi:[1,0]
	v_pk_mul_f32 v[104:105], v[104:105], v[114:115] op_sel_hi:[1,0]
	s_and_saveexec_b64 s[6:7], vcc
	s_cbranch_execz .LBB0_814
	v_lshl_add_u32 v115, v124, 2, v113
	global_load_dwordx4 v[116:119], v115, s[50:51] offset:16
	global_load_dwordx4 v[146:149], v115, s[50:51]
	s_waitcnt vmcnt(0)
	v_pk_mul_f32 v[154:155], v[104:105], v[116:117] op_sel:[1,1] op_sel_hi:[0,1]
	v_pk_mul_f32 v[126:127], v[108:109], v[146:147] op_sel:[1,1] op_sel_hi:[0,1]
	v_pk_mul_f32 v[120:121], v[108:109], v[146:147]
	v_pk_fma_f32 v[108:109], v[108:109], v[146:147], v[126:127] op_sel_hi:[1,0,1]
	s_nop 0
	v_mul_f32_e32 v108, v111, v149
	v_pk_fma_f32 v[146:147], v[110:111], v[148:149], v[108:109] op_sel_hi:[1,1,0] neg_lo:[0,0,1] neg_hi:[0,0,1]
	v_mul_f32_e32 v108, v110, v149
	v_pk_fma_f32 v[148:149], v[110:111], v[148:149], v[108:109] op_sel:[1,0,0] op_sel_hi:[0,1,0]
	v_pk_mul_f32 v[110:111], v[104:105], v[116:117]
	v_pk_fma_f32 v[104:105], v[104:105], v[116:117], v[154:155] op_sel_hi:[1,0,1]
	v_sub_f32_e32 v108, v120, v126
	v_mul_f32_e32 v104, v107, v119
	v_pk_fma_f32 v[116:117], v[106:107], v[118:119], v[104:105] op_sel_hi:[1,1,0] neg_lo:[0,0,1] neg_hi:[0,0,1]
	v_mul_f32_e32 v104, v106, v119
	v_pk_fma_f32 v[118:119], v[106:107], v[118:119], v[104:105] op_sel:[1,0,0] op_sel_hi:[0,1,0]
	v_sub_f32_e32 v104, v110, v154
	v_mov_b32_e32 v106, v116
	v_mov_b32_e32 v107, v118
	v_mov_b32_e32 v110, v146
	v_mov_b32_e32 v111, v148

; DI float ss_get(const ssacc_t* p) { const ssacc_t v = *p; return (float)(unsigned)(v >> 32) + (float)(unsigned)(v & 0xffffffffull) * 2.3283064365386963e-10f; }
; DI u32x4 pack8(const f32x4& a, const f32x4& b) { u32x4 w; w.x = cvtpk(a[0], a[1]); w.y = cvtpk(a[2], a[3]); w.z = cvtpk(b[0], b[1]); w.w = cvtpk(b[2], b[3]); return w; }
;     DI const bf16_t* Q() const { return (const bf16_t*)(ws + WS_Q); }
;     DI void operator()(const Acc& acc, const Unit& u, int wr, int wc, int fr, int fq) const {
;     ...
;                 asm volatile("" ::: "memory");
;                 const int row = u.pm * 256 + ai * 128 + wr * 64 + m * 16 + fr;
;                 const float rs = rsqrtf(ss_get(ssq + row) * (1.f / 512.f) + EPS_) * QSCALE_MLA;
; #pragma unroll
;                 for (int bj = 0; bj < 2; ++bj) {
;                     f32x4 v0 = acc[ai][bj][m][0] * rs, v1 = acc[ai][bj][m][1] * rs;
;                     const int c0 = u.pn * 256 + bj * 128 + wc * 32 + 8 * fq;
;                     const int w = c0 % 192;
;                     if (w >= 128) rope8(v0, v1, rope, row & 2047, (w - 128) >> 1);
;                     *(u32x4*)(Q + (size_t)row * 1536 + c0) = pack8(v0, v1);
;                 }
.LBB0_816:
	s_or_b64 exec, exec, s[6:7]
	v_cvt_pk_bf16_f32 v100, v100, v101
	v_cvt_pk_bf16_f32 v101, v102, v103
	v_cvt_pk_bf16_f32 v102, v96, v97
	v_cvt_pk_bf16_f32 v103, v98, v99
	v_or_b32_e32 v96, 32, v144
	global_store_dwordx4 v[104:105], v[100:103], off offset:256
	v_ashrrev_i32_e32 v97, 31, v96
	s_waitcnt vmcnt(9)
	v_mov_b32_e32 v98, v216
	v_mov_b32_e32 v99, v217
	v_mov_b32_e32 v128, v99
	v_lshlrev_b64 v[100:101], s14, v[128:129]
	v_min_u32_e32 v97, 1, v100
	v_or_b32_e32 v97, v101, v97
	v_cvt_f32_u32_e32 v97, v97
	v_cvt_f32_u32_e32 v98, v98
	v_ldexp_f32 v97, v97, s15
	v_fmac_f32_e32 v97, 0x2f800000, v98
	v_fmamk_f32 v97, v97, 0x3b000000, v195
	v_mul_f32_e32 v98, 0x4b800000, v97
	v_cmp_gt_f32_e64 s[6:7], s27, v97
	s_nop 1
	v_cndmask_b32_e64 v97, v97, v98, s[6:7]
	v_rsq_f32_e32 v98, v97
	v_lshlrev_b32_e32 v97, 8, v96
	v_and_b32_e32 v97, 0x7ef00, v97
	v_add_u32_e32 v97, 0xfffffe00, v97
	v_mul_f32_e32 v99, 0x45800000, v98
	v_cndmask_b32_e64 v98, v98, v99, s[6:7]
	v_mul_f32_e32 v98, 0x3dd53b94, v98
	v_pk_mul_f32 v[94:95], v[94:95], v[98:99] op_sel_hi:[1,0]
	v_pk_mul_f32 v[92:93], v[92:93], v[98:99] op_sel_hi:[1,0]
	v_pk_mul_f32 v[90:91], v[90:91], v[98:99] op_sel_hi:[1,0]
	v_pk_mul_f32 v[88:89], v[88:89], v[98:99] op_sel_hi:[1,0]
	s_and_saveexec_b64 s[6:7], vcc
	s_cbranch_execz .LBB0_818
	v_lshl_add_u32 v99, v124, 2, v97
	global_load_dwordx4 v[100:103], v99, s[50:51] offset:16
	global_load_dwordx4 v[104:107], v99, s[50:51]
	s_waitcnt vmcnt(0)
	v_pk_mul_f32 v[112:113], v[88:89], v[100:101] op_sel:[1,1] op_sel_hi:[0,1]
	v_pk_mul_f32 v[110:111], v[92:93], v[104:105] op_sel:[1,1] op_sel_hi:[0,1]
	v_pk_mul_f32 v[108:109], v[92:93], v[104:105]
	v_pk_fma_f32 v[92:93], v[92:93], v[104:105], v[110:111] op_sel_hi:[1,0,1]
	s_nop 0
	v_mul_f32_e32 v92, v95, v107
	v_pk_fma_f32 v[104:105], v[94:95], v[106:107], v[92:93] op_sel_hi:[1,1,0] neg_lo:[0,0,1] neg_hi:[0,0,1]
	v_mul_f32_e32 v92, v94, v107
	v_pk_fma_f32 v[106:107], v[94:95], v[106:107], v[92:93] op_sel:[1,0,0] op_sel_hi:[0,1,0]
	v_pk_mul_f32 v[94:95], v[88:89], v[100:101]
	v_pk_fma_f32 v[88:89], v[88:89], v[100:101], v[112:113] op_sel_hi:[1,0,1]
	v_sub_f32_e32 v92, v108, v110
	v_mul_f32_e32 v88, v91, v103
	v_pk_fma_f32 v[100:101], v[90:91], v[102:103], v[88:89] op_sel_hi:[1,1,0] neg_lo:[0,0,1] neg_hi:[0,0,1]
	v_mul_f32_e32 v88, v90, v103
	v_pk_fma_f32 v[102:103], v[90:91], v[102:103], v[88:89] op_sel:[1,0,0] op_sel_hi:[0,1,0]
	v_sub_f32_e32 v88, v94, v112
	v_mov_b32_e32 v90, v100
	v_mov_b32_e32 v91, v102
	v_mov_b32_e32 v94, v104
	v_mov_b32_e32 v95, v106

; DI float ss_get(const ssacc_t* p) { const ssacc_t v = *p; return (float)(unsigned)(v >> 32) + (float)(unsigned)(v & 0xffffffffull) * 2.3283064365386963e-10f; }
; DI u32x4 pack8(const f32x4& a, const f32x4& b) { u32x4 w; w.x = cvtpk(a[0], a[1]); w.y = cvtpk(a[2], a[3]); w.z = cvtpk(b[0], b[1]); w.w = cvtpk(b[2], b[3]); return w; }
;     DI const bf16_t* Q() const { return (const bf16_t*)(ws + WS_Q); }
;     DI void operator()(const Acc& acc, const Unit& u, int wr, int wc, int fr, int fq) const {
;     ...
;                 asm volatile("" ::: "memory");
;                 const int row = u.pm * 256 + ai * 128 + wr * 64 + m * 16 + fr;
;                 const float rs = rsqrtf(ss_get(ssq + row) * (1.f / 512.f) + EPS_) * QSCALE_MLA;
; #pragma unroll
;                 for (int bj = 0; bj < 2; ++bj) {
;                     f32x4 v0 = acc[ai][bj][m][0] * rs, v1 = acc[ai][bj][m][1] * rs;
;                     const int c0 = u.pn * 256 + bj * 128 + wc * 32 + 8 * fq;
;                     const int w = c0 % 192;
;                     if (w >= 128) rope8(v0, v1, rope, row & 2047, (w - 128) >> 1);
;                     *(u32x4*)(Q + (size_t)row * 1536 + c0) = pack8(v0, v1);
;                 }
.LBB0_820:
	s_or_b64 exec, exec, s[6:7]
	v_cvt_pk_bf16_f32 v84, v84, v85
	v_cvt_pk_bf16_f32 v85, v86, v87
	v_cvt_pk_bf16_f32 v86, v80, v81
	v_cvt_pk_bf16_f32 v87, v82, v83
	v_or_b32_e32 v80, 48, v144
	global_store_dwordx4 v[88:89], v[84:87], off offset:256
	v_ashrrev_i32_e32 v81, 31, v80
	s_waitcnt vmcnt(10)
	v_mov_b32_e32 v82, v218
	v_mov_b32_e32 v83, v219
	v_mov_b32_e32 v128, v83
	v_lshlrev_b64 v[84:85], s14, v[128:129]
	v_min_u32_e32 v81, 1, v84
	v_or_b32_e32 v81, v85, v81
	v_cvt_f32_u32_e32 v81, v81
	v_cvt_f32_u32_e32 v82, v82
	v_ldexp_f32 v81, v81, s15
	v_fmac_f32_e32 v81, 0x2f800000, v82
	v_fmamk_f32 v81, v81, 0x3b000000, v195
	v_mul_f32_e32 v82, 0x4b800000, v81
	v_cmp_gt_f32_e64 s[6:7], s27, v81
	s_nop 1
	v_cndmask_b32_e64 v81, v81, v82, s[6:7]
	v_rsq_f32_e32 v82, v81
	v_lshlrev_b32_e32 v81, 8, v80
	v_and_b32_e32 v81, 0x7ff00, v81
	v_add_u32_e32 v81, 0xfffffe00, v81
	v_mul_f32_e32 v83, 0x45800000, v82
	v_cndmask_b32_e64 v82, v82, v83, s[6:7]
	v_mul_f32_e32 v82, 0x3dd53b94, v82
	v_pk_mul_f32 v[78:79], v[78:79], v[82:83] op_sel_hi:[1,0]
	v_pk_mul_f32 v[76:77], v[76:77], v[82:83] op_sel_hi:[1,0]
	v_pk_mul_f32 v[74:75], v[74:75], v[82:83] op_sel_hi:[1,0]
	v_pk_mul_f32 v[72:73], v[72:73], v[82:83] op_sel_hi:[1,0]
	s_and_saveexec_b64 s[6:7], vcc
	s_cbranch_execz .LBB0_822
	v_lshl_add_u32 v83, v124, 2, v81
	global_load_dwordx4 v[84:87], v83, s[50:51] offset:16
	global_load_dwordx4 v[88:91], v83, s[50:51]
	s_waitcnt vmcnt(0)
	v_pk_mul_f32 v[96:97], v[72:73], v[84:85] op_sel:[1,1] op_sel_hi:[0,1]
	v_pk_mul_f32 v[94:95], v[76:77], v[88:89] op_sel:[1,1] op_sel_hi:[0,1]
	v_pk_mul_f32 v[92:93], v[76:77], v[88:89]
	v_pk_fma_f32 v[76:77], v[76:77], v[88:89], v[94:95] op_sel_hi:[1,0,1]
	s_nop 0
	v_mul_f32_e32 v76, v79, v91
	v_pk_fma_f32 v[88:89], v[78:79], v[90:91], v[76:77] op_sel_hi:[1,1,0] neg_lo:[0,0,1] neg_hi:[0,0,1]
	v_mul_f32_e32 v76, v78, v91
	v_pk_fma_f32 v[90:91], v[78:79], v[90:91], v[76:77] op_sel:[1,0,0] op_sel_hi:[0,1,0]
	v_pk_mul_f32 v[78:79], v[72:73], v[84:85]
	v_pk_fma_f32 v[72:73], v[72:73], v[84:85], v[96:97] op_sel_hi:[1,0,1]
	v_sub_f32_e32 v76, v92, v94
	v_mul_f32_e32 v72, v75, v87
	v_pk_fma_f32 v[84:85], v[74:75], v[86:87], v[72:73] op_sel_hi:[1,1,0] neg_lo:[0,0,1] neg_hi:[0,0,1]
	v_mul_f32_e32 v72, v74, v87
	v_pk_fma_f32 v[86:87], v[74:75], v[86:87], v[72:73] op_sel:[1,0,0] op_sel_hi:[0,1,0]
	v_sub_f32_e32 v72, v78, v96
	v_mov_b32_e32 v74, v84
	v_mov_b32_e32 v75, v86
	v_mov_b32_e32 v78, v88
	v_mov_b32_e32 v79, v90

; DI float ss_get(const ssacc_t* p) { const ssacc_t v = *p; return (float)(unsigned)(v >> 32) + (float)(unsigned)(v & 0xffffffffull) * 2.3283064365386963e-10f; }
; DI u32x4 pack8(const f32x4& a, const f32x4& b) { u32x4 w; w.x = cvtpk(a[0], a[1]); w.y = cvtpk(a[2], a[3]); w.z = cvtpk(b[0], b[1]); w.w = cvtpk(b[2], b[3]); return w; }
;     DI const bf16_t* Q() const { return (const bf16_t*)(ws + WS_Q); }
;     DI void operator()(const Acc& acc, const Unit& u, int wr, int wc, int fr, int fq) const {
;     ...
;                 asm volatile("" ::: "memory");
;                 const int row = u.pm * 256 + ai * 128 + wr * 64 + m * 16 + fr;
;                 const float rs = rsqrtf(ss_get(ssq + row) * (1.f / 512.f) + EPS_) * QSCALE_MLA;
; #pragma unroll
;                 for (int bj = 0; bj < 2; ++bj) {
;                     f32x4 v0 = acc[ai][bj][m][0] * rs, v1 = acc[ai][bj][m][1] * rs;
;                     const int c0 = u.pn * 256 + bj * 128 + wc * 32 + 8 * fq;
;                     const int w = c0 % 192;
;                     if (w >= 128) rope8(v0, v1, rope, row & 2047, (w - 128) >> 1);
;                     *(u32x4*)(Q + (size_t)row * 1536 + c0) = pack8(v0, v1);
;                 }
.LBB0_824:
	s_or_b64 exec, exec, s[6:7]
	v_cvt_pk_bf16_f32 v68, v68, v69
	v_cvt_pk_bf16_f32 v69, v70, v71
	v_cvt_pk_bf16_f32 v70, v64, v65
	v_cvt_pk_bf16_f32 v71, v66, v67
	v_add_u32_e32 v64, 0x80, v144
	global_store_dwordx4 v[72:73], v[68:71], off offset:256
	v_ashrrev_i32_e32 v65, 31, v64
	s_waitcnt vmcnt(11)
	v_mov_b32_e32 v66, v220
	v_mov_b32_e32 v67, v221
	v_mov_b32_e32 v128, v67
	v_lshlrev_b64 v[68:69], s14, v[128:129]
	v_min_u32_e32 v65, 1, v68
	v_or_b32_e32 v65, v69, v65
	v_cvt_f32_u32_e32 v65, v65
	v_cvt_f32_u32_e32 v66, v66
	v_ldexp_f32 v65, v65, s15
	v_fmac_f32_e32 v65, 0x2f800000, v66
	v_fmamk_f32 v65, v65, 0x3b000000, v195
	v_mul_f32_e32 v66, 0x4b800000, v65
	v_cmp_gt_f32_e64 s[6:7], s27, v65
	s_nop 1
	v_cndmask_b32_e64 v65, v65, v66, s[6:7]
	v_rsq_f32_e32 v66, v65
	v_lshlrev_b32_e32 v65, 8, v64
	v_and_b32_e32 v65, 0x7cf00, v65
	v_add_u32_e32 v65, 0xfffffe00, v65
	v_mul_f32_e32 v67, 0x45800000, v66
	v_cndmask_b32_e64 v66, v66, v67, s[6:7]
	v_mul_f32_e32 v66, 0x3dd53b94, v66
	v_pk_mul_f32 v[62:63], v[62:63], v[66:67] op_sel_hi:[1,0]
	v_pk_mul_f32 v[60:61], v[60:61], v[66:67] op_sel_hi:[1,0]
	v_pk_mul_f32 v[58:59], v[58:59], v[66:67] op_sel_hi:[1,0]
	v_pk_mul_f32 v[56:57], v[56:57], v[66:67] op_sel_hi:[1,0]
	s_and_saveexec_b64 s[6:7], vcc
	s_cbranch_execz .LBB0_826
	v_lshl_add_u32 v67, v124, 2, v65
	global_load_dwordx4 v[68:71], v67, s[50:51] offset:16
	global_load_dwordx4 v[72:75], v67, s[50:51]
	s_waitcnt vmcnt(0)
	v_pk_mul_f32 v[80:81], v[56:57], v[68:69] op_sel:[1,1] op_sel_hi:[0,1]
	v_pk_mul_f32 v[78:79], v[60:61], v[72:73] op_sel:[1,1] op_sel_hi:[0,1]
	v_pk_mul_f32 v[76:77], v[60:61], v[72:73]
	v_pk_fma_f32 v[60:61], v[60:61], v[72:73], v[78:79] op_sel_hi:[1,0,1]
	s_nop 0
	v_mul_f32_e32 v60, v63, v75
	v_pk_fma_f32 v[72:73], v[62:63], v[74:75], v[60:61] op_sel_hi:[1,1,0] neg_lo:[0,0,1] neg_hi:[0,0,1]
	v_mul_f32_e32 v60, v62, v75
	v_pk_fma_f32 v[74:75], v[62:63], v[74:75], v[60:61] op_sel:[1,0,0] op_sel_hi:[0,1,0]
	v_pk_mul_f32 v[62:63], v[56:57], v[68:69]
	v_pk_fma_f32 v[56:57], v[56:57], v[68:69], v[80:81] op_sel_hi:[1,0,1]
	v_sub_f32_e32 v60, v76, v78
	v_mul_f32_e32 v56, v59, v71
	v_pk_fma_f32 v[68:69], v[58:59], v[70:71], v[56:57] op_sel_hi:[1,1,0] neg_lo:[0,0,1] neg_hi:[0,0,1]
	v_mul_f32_e32 v56, v58, v71
	v_pk_fma_f32 v[70:71], v[58:59], v[70:71], v[56:57] op_sel:[1,0,0] op_sel_hi:[0,1,0]
	v_sub_f32_e32 v56, v62, v80
	v_mov_b32_e32 v58, v68
	v_mov_b32_e32 v59, v70
	v_mov_b32_e32 v62, v72
	v_mov_b32_e32 v63, v74

; DI float ss_get(const ssacc_t* p) { const ssacc_t v = *p; return (float)(unsigned)(v >> 32) + (float)(unsigned)(v & 0xffffffffull) * 2.3283064365386963e-10f; }
; DI u32x4 pack8(const f32x4& a, const f32x4& b) { u32x4 w; w.x = cvtpk(a[0], a[1]); w.y = cvtpk(a[2], a[3]); w.z = cvtpk(b[0], b[1]); w.w = cvtpk(b[2], b[3]); return w; }
;     DI const bf16_t* Q() const { return (const bf16_t*)(ws + WS_Q); }
;     DI void operator()(const Acc& acc, const Unit& u, int wr, int wc, int fr, int fq) const {
;     ...
;                 asm volatile("" ::: "memory");
;                 const int row = u.pm * 256 + ai * 128 + wr * 64 + m * 16 + fr;
;                 const float rs = rsqrtf(ss_get(ssq + row) * (1.f / 512.f) + EPS_) * QSCALE_MLA;
; #pragma unroll
;                 for (int bj = 0; bj < 2; ++bj) {
;                     f32x4 v0 = acc[ai][bj][m][0] * rs, v1 = acc[ai][bj][m][1] * rs;
;                     const int c0 = u.pn * 256 + bj * 128 + wc * 32 + 8 * fq;
;                     const int w = c0 % 192;
;                     if (w >= 128) rope8(v0, v1, rope, row & 2047, (w - 128) >> 1);
;                     *(u32x4*)(Q + (size_t)row * 1536 + c0) = pack8(v0, v1);
;                 }
.LBB0_828:
	s_or_b64 exec, exec, s[6:7]
	v_cvt_pk_bf16_f32 v52, v52, v53
	v_cvt_pk_bf16_f32 v53, v54, v55
	v_cvt_pk_bf16_f32 v54, v48, v49
	v_cvt_pk_bf16_f32 v55, v50, v51
	v_add_u32_e32 v48, 0x90, v144
	global_store_dwordx4 v[56:57], v[52:55], off offset:256
	v_ashrrev_i32_e32 v49, 31, v48
	s_waitcnt vmcnt(12)
	v_mov_b32_e32 v50, v222
	v_mov_b32_e32 v51, v223
	v_mov_b32_e32 v128, v51
	v_lshlrev_b64 v[52:53], s14, v[128:129]
	v_min_u32_e32 v49, 1, v52
	v_or_b32_e32 v49, v53, v49
	v_cvt_f32_u32_e32 v49, v49
	v_cvt_f32_u32_e32 v50, v50
	v_ldexp_f32 v49, v49, s15
	v_fmac_f32_e32 v49, 0x2f800000, v50
	v_fmamk_f32 v49, v49, 0x3b000000, v195
	v_mul_f32_e32 v50, 0x4b800000, v49
	v_cmp_gt_f32_e64 s[6:7], s27, v49
	s_nop 1
	v_cndmask_b32_e64 v49, v49, v50, s[6:7]
	v_rsq_f32_e32 v50, v49
	v_lshlrev_b32_e32 v49, 8, v48
	v_and_b32_e32 v49, 0x7df00, v49
	v_add_u32_e32 v49, 0xfffffe00, v49
	v_mul_f32_e32 v51, 0x45800000, v50
	v_cndmask_b32_e64 v50, v50, v51, s[6:7]
	v_mul_f32_e32 v50, 0x3dd53b94, v50
	v_pk_mul_f32 v[46:47], v[46:47], v[50:51] op_sel_hi:[1,0]
	v_pk_mul_f32 v[44:45], v[44:45], v[50:51] op_sel_hi:[1,0]
	v_pk_mul_f32 v[42:43], v[42:43], v[50:51] op_sel_hi:[1,0]
	v_pk_mul_f32 v[40:41], v[40:41], v[50:51] op_sel_hi:[1,0]
	s_and_saveexec_b64 s[6:7], vcc
	s_cbranch_execz .LBB0_830
	v_lshl_add_u32 v51, v124, 2, v49
	global_load_dwordx4 v[52:55], v51, s[50:51] offset:16
	global_load_dwordx4 v[56:59], v51, s[50:51]
	s_waitcnt vmcnt(0)
	v_pk_mul_f32 v[64:65], v[40:41], v[52:53] op_sel:[1,1] op_sel_hi:[0,1]
	v_pk_mul_f32 v[62:63], v[44:45], v[56:57] op_sel:[1,1] op_sel_hi:[0,1]
	v_pk_mul_f32 v[60:61], v[44:45], v[56:57]
	v_pk_fma_f32 v[44:45], v[44:45], v[56:57], v[62:63] op_sel_hi:[1,0,1]
	s_nop 0
	v_mul_f32_e32 v44, v47, v59
	v_pk_fma_f32 v[56:57], v[46:47], v[58:59], v[44:45] op_sel_hi:[1,1,0] neg_lo:[0,0,1] neg_hi:[0,0,1]
	v_mul_f32_e32 v44, v46, v59
	v_pk_fma_f32 v[58:59], v[46:47], v[58:59], v[44:45] op_sel:[1,0,0] op_sel_hi:[0,1,0]
	v_pk_mul_f32 v[46:47], v[40:41], v[52:53]
	v_pk_fma_f32 v[40:41], v[40:41], v[52:53], v[64:65] op_sel_hi:[1,0,1]
	v_sub_f32_e32 v44, v60, v62
	v_mul_f32_e32 v40, v43, v55
	v_pk_fma_f32 v[52:53], v[42:43], v[54:55], v[40:41] op_sel_hi:[1,1,0] neg_lo:[0,0,1] neg_hi:[0,0,1]
	v_mul_f32_e32 v40, v42, v55
	v_pk_fma_f32 v[54:55], v[42:43], v[54:55], v[40:41] op_sel:[1,0,0] op_sel_hi:[0,1,0]
	v_sub_f32_e32 v40, v46, v64
	v_mov_b32_e32 v42, v52
	v_mov_b32_e32 v43, v54
	v_mov_b32_e32 v46, v56
	v_mov_b32_e32 v47, v58

; DI float ss_get(const ssacc_t* p) { const ssacc_t v = *p; return (float)(unsigned)(v >> 32) + (float)(unsigned)(v & 0xffffffffull) * 2.3283064365386963e-10f; }
; DI u32x4 pack8(const f32x4& a, const f32x4& b) { u32x4 w; w.x = cvtpk(a[0], a[1]); w.y = cvtpk(a[2], a[3]); w.z = cvtpk(b[0], b[1]); w.w = cvtpk(b[2], b[3]); return w; }
;     DI const bf16_t* Q() const { return (const bf16_t*)(ws + WS_Q); }
;     DI void operator()(const Acc& acc, const Unit& u, int wr, int wc, int fr, int fq) const {
;     ...
;                 asm volatile("" ::: "memory");
;                 const int row = u.pm * 256 + ai * 128 + wr * 64 + m * 16 + fr;
;                 const float rs = rsqrtf(ss_get(ssq + row) * (1.f / 512.f) + EPS_) * QSCALE_MLA;
; #pragma unroll
;                 for (int bj = 0; bj < 2; ++bj) {
;                     f32x4 v0 = acc[ai][bj][m][0] * rs, v1 = acc[ai][bj][m][1] * rs;
;                     const int c0 = u.pn * 256 + bj * 128 + wc * 32 + 8 * fq;
;                     const int w = c0 % 192;
;                     if (w >= 128) rope8(v0, v1, rope, row & 2047, (w - 128) >> 1);
;                     *(u32x4*)(Q + (size_t)row * 1536 + c0) = pack8(v0, v1);
;                 }
.LBB0_832:
	s_or_b64 exec, exec, s[6:7]
	v_cvt_pk_bf16_f32 v36, v36, v37
	v_cvt_pk_bf16_f32 v37, v38, v39
	v_cvt_pk_bf16_f32 v38, v32, v33
	v_cvt_pk_bf16_f32 v39, v34, v35
	v_add_u32_e32 v32, 0xa0, v144
	global_store_dwordx4 v[40:41], v[36:39], off offset:256
	v_ashrrev_i32_e32 v33, 31, v32
	s_waitcnt vmcnt(13)
	v_mov_b32_e32 v34, v224
	v_mov_b32_e32 v35, v225
	v_mov_b32_e32 v128, v35
	v_lshlrev_b64 v[36:37], s14, v[128:129]
	v_min_u32_e32 v33, 1, v36
	v_or_b32_e32 v33, v37, v33
	v_cvt_f32_u32_e32 v33, v33
	v_cvt_f32_u32_e32 v34, v34
	v_ldexp_f32 v33, v33, s15
	v_fmac_f32_e32 v33, 0x2f800000, v34
	v_fmamk_f32 v33, v33, 0x3b000000, v195
	v_mul_f32_e32 v34, 0x4b800000, v33
	v_cmp_gt_f32_e64 s[6:7], s27, v33
	s_nop 1
	v_cndmask_b32_e64 v33, v33, v34, s[6:7]
	v_rsq_f32_e32 v34, v33
	v_lshlrev_b32_e32 v33, 8, v32
	v_and_b32_e32 v33, 0x7ef00, v33
	v_add_u32_e32 v33, 0xfffffe00, v33
	v_mul_f32_e32 v35, 0x45800000, v34
	v_cndmask_b32_e64 v34, v34, v35, s[6:7]
	v_mul_f32_e32 v34, 0x3dd53b94, v34
	v_pk_mul_f32 v[30:31], v[30:31], v[34:35] op_sel_hi:[1,0]
	v_pk_mul_f32 v[28:29], v[28:29], v[34:35] op_sel_hi:[1,0]
	v_pk_mul_f32 v[26:27], v[26:27], v[34:35] op_sel_hi:[1,0]
	v_pk_mul_f32 v[24:25], v[24:25], v[34:35] op_sel_hi:[1,0]
	s_and_saveexec_b64 s[6:7], vcc
	s_cbranch_execz .LBB0_834
	v_lshl_add_u32 v35, v124, 2, v33
	global_load_dwordx4 v[36:39], v35, s[50:51] offset:16
	global_load_dwordx4 v[40:43], v35, s[50:51]
	s_waitcnt vmcnt(0)
	v_pk_mul_f32 v[48:49], v[24:25], v[36:37] op_sel:[1,1] op_sel_hi:[0,1]
	v_pk_mul_f32 v[46:47], v[28:29], v[40:41] op_sel:[1,1] op_sel_hi:[0,1]
	v_pk_mul_f32 v[44:45], v[28:29], v[40:41]
	v_pk_fma_f32 v[28:29], v[28:29], v[40:41], v[46:47] op_sel_hi:[1,0,1]
	s_nop 0
	v_mul_f32_e32 v28, v31, v43
	v_pk_fma_f32 v[40:41], v[30:31], v[42:43], v[28:29] op_sel_hi:[1,1,0] neg_lo:[0,0,1] neg_hi:[0,0,1]
	v_mul_f32_e32 v28, v30, v43
	v_pk_fma_f32 v[42:43], v[30:31], v[42:43], v[28:29] op_sel:[1,0,0] op_sel_hi:[0,1,0]
	v_pk_mul_f32 v[30:31], v[24:25], v[36:37]
	v_pk_fma_f32 v[24:25], v[24:25], v[36:37], v[48:49] op_sel_hi:[1,0,1]
	v_sub_f32_e32 v28, v44, v46
	v_mul_f32_e32 v24, v27, v39
	v_pk_fma_f32 v[36:37], v[26:27], v[38:39], v[24:25] op_sel_hi:[1,1,0] neg_lo:[0,0,1] neg_hi:[0,0,1]
	v_mul_f32_e32 v24, v26, v39
	v_pk_fma_f32 v[38:39], v[26:27], v[38:39], v[24:25] op_sel:[1,0,0] op_sel_hi:[0,1,0]
	v_sub_f32_e32 v24, v30, v48
	v_mov_b32_e32 v26, v36
	v_mov_b32_e32 v27, v38
	v_mov_b32_e32 v30, v40
	v_mov_b32_e32 v31, v42

; DI float ss_get(const ssacc_t* p) { const ssacc_t v = *p; return (float)(unsigned)(v >> 32) + (float)(unsigned)(v & 0xffffffffull) * 2.3283064365386963e-10f; }
; DI u32x4 pack8(const f32x4& a, const f32x4& b) { u32x4 w; w.x = cvtpk(a[0], a[1]); w.y = cvtpk(a[2], a[3]); w.z = cvtpk(b[0], b[1]); w.w = cvtpk(b[2], b[3]); return w; }
;     DI const bf16_t* Q() const { return (const bf16_t*)(ws + WS_Q); }
;     DI void operator()(const Acc& acc, const Unit& u, int wr, int wc, int fr, int fq) const {
;     ...
;                 asm volatile("" ::: "memory");
;                 const int row = u.pm * 256 + ai * 128 + wr * 64 + m * 16 + fr;
;                 const float rs = rsqrtf(ss_get(ssq + row) * (1.f / 512.f) + EPS_) * QSCALE_MLA;
; #pragma unroll
;                 for (int bj = 0; bj < 2; ++bj) {
;                     f32x4 v0 = acc[ai][bj][m][0] * rs, v1 = acc[ai][bj][m][1] * rs;
;                     const int c0 = u.pn * 256 + bj * 128 + wc * 32 + 8 * fq;
;                     const int w = c0 % 192;
;                     if (w >= 128) rope8(v0, v1, rope, row & 2047, (w - 128) >> 1);
;                     *(u32x4*)(Q + (size_t)row * 1536 + c0) = pack8(v0, v1);
;                 }
.LBB0_836:
	s_or_b64 exec, exec, s[6:7]
	v_cvt_pk_bf16_f32 v20, v20, v21
	v_cvt_pk_bf16_f32 v21, v22, v23
	v_cvt_pk_bf16_f32 v22, v16, v17
	v_cvt_pk_bf16_f32 v23, v18, v19
	v_add_u32_e32 v16, 0xb0, v144
	global_store_dwordx4 v[24:25], v[20:23], off offset:256
	v_ashrrev_i32_e32 v17, 31, v16
	s_waitcnt vmcnt(14)
	v_mov_b32_e32 v18, v226
	v_mov_b32_e32 v19, v227
	v_mov_b32_e32 v128, v19
	v_lshlrev_b64 v[20:21], s14, v[128:129]
	v_min_u32_e32 v17, 1, v20
	v_or_b32_e32 v17, v21, v17
	v_cvt_f32_u32_e32 v17, v17
	v_cvt_f32_u32_e32 v18, v18
	v_ldexp_f32 v17, v17, s15
	v_fmac_f32_e32 v17, 0x2f800000, v18
	v_fmamk_f32 v17, v17, 0x3b000000, v195
	v_mul_f32_e32 v18, 0x4b800000, v17
	v_cmp_gt_f32_e64 s[6:7], s27, v17
	s_nop 1
	v_cndmask_b32_e64 v17, v17, v18, s[6:7]
	v_rsq_f32_e32 v18, v17
	v_lshlrev_b32_e32 v17, 8, v16
	v_and_b32_e32 v17, 0x7ff00, v17
	v_add_u32_e32 v17, 0xfffffe00, v17
	v_mul_f32_e32 v19, 0x45800000, v18
	v_cndmask_b32_e64 v18, v18, v19, s[6:7]
	v_mul_f32_e32 v18, 0x3dd53b94, v18
	v_pk_mul_f32 v[14:15], v[14:15], v[18:19] op_sel_hi:[1,0]
	v_pk_mul_f32 v[12:13], v[12:13], v[18:19] op_sel_hi:[1,0]
	v_pk_mul_f32 v[10:11], v[10:11], v[18:19] op_sel_hi:[1,0]
	v_pk_mul_f32 v[8:9], v[8:9], v[18:19] op_sel_hi:[1,0]
	s_and_saveexec_b64 s[6:7], vcc
	s_cbranch_execz .LBB0_838
	v_lshl_add_u32 v19, v124, 2, v17
	global_load_dwordx4 v[20:23], v19, s[50:51] offset:16
	global_load_dwordx4 v[24:27], v19, s[50:51]
	s_waitcnt vmcnt(0)
	v_pk_mul_f32 v[32:33], v[8:9], v[20:21] op_sel:[1,1] op_sel_hi:[0,1]
	v_pk_mul_f32 v[30:31], v[12:13], v[24:25] op_sel:[1,1] op_sel_hi:[0,1]
	v_pk_mul_f32 v[28:29], v[12:13], v[24:25]
	v_pk_fma_f32 v[12:13], v[12:13], v[24:25], v[30:31] op_sel_hi:[1,0,1]
	s_nop 0
	v_mul_f32_e32 v12, v15, v27
	v_pk_fma_f32 v[24:25], v[14:15], v[26:27], v[12:13] op_sel_hi:[1,1,0] neg_lo:[0,0,1] neg_hi:[0,0,1]
	v_mul_f32_e32 v12, v14, v27
	v_pk_fma_f32 v[26:27], v[14:15], v[26:27], v[12:13] op_sel:[1,0,0] op_sel_hi:[0,1,0]
	v_pk_mul_f32 v[14:15], v[8:9], v[20:21]
	v_pk_fma_f32 v[8:9], v[8:9], v[20:21], v[32:33] op_sel_hi:[1,0,1]
	v_sub_f32_e32 v12, v28, v30
	v_mul_f32_e32 v8, v11, v23
	v_pk_fma_f32 v[20:21], v[10:11], v[22:23], v[8:9] op_sel_hi:[1,1,0] neg_lo:[0,0,1] neg_hi:[0,0,1]
	v_mul_f32_e32 v8, v10, v23
	v_pk_fma_f32 v[22:23], v[10:11], v[22:23], v[8:9] op_sel:[1,0,0] op_sel_hi:[0,1,0]
	v_sub_f32_e32 v8, v14, v32
	v_mov_b32_e32 v10, v20
	v_mov_b32_e32 v11, v22
	v_mov_b32_e32 v14, v24
	v_mov_b32_e32 v15, v26

; DI float ss_get(const ssacc_t* p) { const ssacc_t v = *p; return (float)(unsigned)(v >> 32) + (float)(unsigned)(v & 0xffffffffull) * 2.3283064365386963e-10f; }
; DI u32x4 pack8(const f32x4& a, const f32x4& b) { u32x4 w; w.x = cvtpk(a[0], a[1]); w.y = cvtpk(a[2], a[3]); w.z = cvtpk(b[0], b[1]); w.w = cvtpk(b[2], b[3]); return w; }
;     DI const bf16_t* KV() const { return (const bf16_t*)(ws + WS_KV); }
;     DI void operator()(const Acc& acc, const Unit& u, int wr, int wc, int fr, int fq) const {
; #pragma unroll
;         for (int ai = 0; ai < 2; ++ai)
; #pragma unroll
;             for (int m = 0; m < 4; ++m) {
;                 asm volatile("" ::: "memory");
;                 const int row = u.pm * 256 + ai * 128 + wr * 64 + m * 16 + fr;
;                 const float rs = rsqrtf(ss_get(sskv + row) * (1.f / 256.f) + EPS_);
; #pragma unroll
;                 for (int bj = 0; bj < 2; ++bj) {
;                     const f32x4 v0 = acc[ai][bj][m][0] * rs, v1 = acc[ai][bj][m][1] * rs;
;                     const int c0 = u.pn * 256 + bj * 128 + wc * 32 + 8 * fq;
;                     *(u32x4*)(KV + (size_t)row * 2048 + c0) = pack8(v0, v1);
;                 }
.LBB0_865:
	v_lshl_add_u32 v142, s62, 8, v144
	v_ashrrev_i32_e32 v143, 31, v142
	v_lshl_add_u64 v[150:151], v[142:143], 3, s[44:45]
	global_load_dwordx2 v[212:213], v[150:151], off
	global_load_dwordx2 v[214:215], v[150:151], off offset:128
	global_load_dwordx2 v[216:217], v[150:151], off offset:256
	global_load_dwordx2 v[218:219], v[150:151], off offset:384
	global_load_dwordx2 v[220:221], v[150:151], off offset:1024
	global_load_dwordx2 v[222:223], v[150:151], off offset:1152
	global_load_dwordx2 v[224:225], v[150:151], off offset:1280
	global_load_dwordx2 v[226:227], v[150:151], off offset:1408
	s_min_u32 s14, s88, 32
	s_sub_i32 s15, 32, s14
	v_lshl_or_b32 v148, s61, 8, v146
	s_waitcnt vmcnt(7)
	v_mov_b32_e32 v150, v212
	v_mov_b32_e32 v151, v213
	v_mov_b32_e32 v128, v151
	v_lshlrev_b64 v[152:153], s14, v[128:129]
	v_min_u32_e32 v128, 1, v152
	v_or_b32_e32 v128, v153, v128
	v_cvt_f32_u32_e32 v128, v128
	v_cvt_f32_u32_e32 v149, v150
	v_lshlrev_b64 v[150:151], 12, v[142:143]
	v_ldexp_f32 v128, v128, s15
	v_fmac_f32_e32 v128, 0x2f800000, v149
	v_fmamk_f32 v128, v128, 0x3b800000, v195
	v_cmp_gt_f32_e32 vcc, s27, v128
	v_mul_f32_e32 v149, 0x4b800000, v128
	s_nop 0
	v_cndmask_b32_e32 v128, v128, v149, vcc
	v_rsq_f32_e32 v128, v128
	s_nop 0
	v_mul_f32_e32 v149, 0x45800000, v128
	v_cndmask_b32_e32 v128, v128, v149, vcc
	v_pk_mul_f32 v[120:121], v[120:121], v[128:129] op_sel_hi:[1,0]
	v_pk_mul_f32 v[126:127], v[126:127], v[128:129] op_sel_hi:[1,0]
	v_pk_mul_f32 v[124:125], v[124:125], v[128:129] op_sel_hi:[1,0]
	v_ashrrev_i32_e32 v149, 31, v148
	v_pk_mul_f32 v[152:153], v[122:123], v[128:129] op_sel_hi:[1,0]
	v_cvt_pk_bf16_f32 v122, v120, v121
	v_cvt_pk_bf16_f32 v124, v124, v125
	v_cvt_pk_bf16_f32 v125, v126, v127
	v_lshl_add_u64 v[126:127], s[48:49], 0, v[150:151]
	v_lshlrev_b64 v[120:121], 1, v[148:149]
	v_cvt_pk_bf16_f32 v123, v152, v153
	v_lshl_add_u64 v[126:127], v[126:127], 0, v[120:121]
	global_store_dwordx4 v[126:127], v[122:125], off
	v_pk_mul_f32 v[118:119], v[118:119], v[128:129] op_sel_hi:[1,0]
	v_pk_mul_f32 v[116:117], v[116:117], v[128:129] op_sel_hi:[1,0]
	v_pk_mul_f32 v[122:123], v[114:115], v[128:129] op_sel_hi:[1,0]
	v_pk_mul_f32 v[114:115], v[112:113], v[128:129] op_sel_hi:[1,0]
	v_cvt_pk_bf16_f32 v112, v116, v117
	v_cvt_pk_bf16_f32 v113, v118, v119
	v_cvt_pk_bf16_f32 v114, v114, v115
	v_cvt_pk_bf16_f32 v115, v122, v123
	global_store_dwordx4 v[126:127], v[112:115], off offset:256
	s_nop 1
	v_or_b32_e32 v112, 16, v142
	v_ashrrev_i32_e32 v113, 31, v112
	v_lshlrev_b64 v[112:113], 12, v[112:113]
	s_waitcnt vmcnt(8)
	v_mov_b32_e32 v114, v214
	v_mov_b32_e32 v115, v215
	v_mov_b32_e32 v128, v115
	v_lshlrev_b64 v[116:117], s14, v[128:129]
	v_min_u32_e32 v115, 1, v116
	v_or_b32_e32 v115, v117, v115
	v_cvt_f32_u32_e32 v115, v115
	v_cvt_f32_u32_e32 v114, v114
	v_ldexp_f32 v115, v115, s15
	v_fmac_f32_e32 v115, 0x2f800000, v114
	v_fmamk_f32 v114, v115, 0x3b800000, v195
	v_cmp_gt_f32_e32 vcc, s27, v114
	v_mul_f32_e32 v115, 0x4b800000, v114
	s_nop 0
	v_cndmask_b32_e32 v114, v114, v115, vcc
	v_rsq_f32_e32 v114, v114
	s_nop 0
	v_mul_f32_e32 v115, 0x45800000, v114
	v_cndmask_b32_e32 v114, v114, v115, vcc
	v_pk_mul_f32 v[108:109], v[108:109], v[114:115] op_sel_hi:[1,0]
	v_pk_mul_f32 v[110:111], v[110:111], v[114:115] op_sel_hi:[1,0]
	v_pk_mul_f32 v[116:117], v[106:107], v[114:115] op_sel_hi:[1,0]
	v_pk_mul_f32 v[106:107], v[104:105], v[114:115] op_sel_hi:[1,0]
	v_cvt_pk_bf16_f32 v104, v108, v109
	v_lshl_add_u64 v[108:109], s[48:49], 0, v[112:113]
	v_cvt_pk_bf16_f32 v105, v110, v111
	v_cvt_pk_bf16_f32 v106, v106, v107
	v_cvt_pk_bf16_f32 v107, v116, v117
	v_lshl_add_u64 v[108:109], v[108:109], 0, v[120:121]
	global_store_dwordx4 v[108:109], v[104:107], off
	v_pk_mul_f32 v[102:103], v[102:103], v[114:115] op_sel_hi:[1,0]
	v_pk_mul_f32 v[100:101], v[100:101], v[114:115] op_sel_hi:[1,0]
	v_pk_mul_f32 v[104:105], v[98:99], v[114:115] op_sel_hi:[1,0]
	v_pk_mul_f32 v[98:99], v[96:97], v[114:115] op_sel_hi:[1,0]
	v_cvt_pk_bf16_f32 v96, v100, v101
	v_cvt_pk_bf16_f32 v97, v102, v103
	v_cvt_pk_bf16_f32 v98, v98, v99
	v_cvt_pk_bf16_f32 v99, v104, v105
	global_store_dwordx4 v[108:109], v[96:99], off offset:256
	s_nop 1
	v_or_b32_e32 v96, 32, v142
	v_ashrrev_i32_e32 v97, 31, v96
	v_lshlrev_b64 v[96:97], 12, v[96:97]
	s_waitcnt vmcnt(9)
	v_mov_b32_e32 v98, v216
	v_mov_b32_e32 v99, v217
	v_mov_b32_e32 v128, v99
	v_lshlrev_b64 v[100:101], s14, v[128:129]
	v_min_u32_e32 v99, 1, v100
	v_or_b32_e32 v99, v101, v99
	v_cvt_f32_u32_e32 v99, v99
	v_cvt_f32_u32_e32 v98, v98
	v_ldexp_f32 v99, v99, s15
	v_fmac_f32_e32 v99, 0x2f800000, v98
	v_fmamk_f32 v98, v99, 0x3b800000, v195
	v_cmp_gt_f32_e32 vcc, s27, v98
	v_mul_f32_e32 v99, 0x4b800000, v98
	s_nop 0
	v_cndmask_b32_e32 v98, v98, v99, vcc
	v_rsq_f32_e32 v98, v98
	s_nop 0
	v_mul_f32_e32 v99, 0x45800000, v98
	v_cndmask_b32_e32 v98, v98, v99, vcc
	v_pk_mul_f32 v[92:93], v[92:93], v[98:99] op_sel_hi:[1,0]
	v_pk_mul_f32 v[94:95], v[94:95], v[98:99] op_sel_hi:[1,0]
	v_pk_mul_f32 v[100:101], v[90:91], v[98:99] op_sel_hi:[1,0]
	v_pk_mul_f32 v[90:91], v[88:89], v[98:99] op_sel_hi:[1,0]
	v_cvt_pk_bf16_f32 v88, v92, v93
	v_lshl_add_u64 v[92:93], s[48:49], 0, v[96:97]
	v_cvt_pk_bf16_f32 v89, v94, v95
	v_cvt_pk_bf16_f32 v90, v90, v91
	v_cvt_pk_bf16_f32 v91, v100, v101
	v_lshl_add_u64 v[92:93], v[92:93], 0, v[120:121]
	global_store_dwordx4 v[92:93], v[88:91], off
	v_pk_mul_f32 v[86:87], v[86:87], v[98:99] op_sel_hi:[1,0]
	v_pk_mul_f32 v[84:85], v[84:85], v[98:99] op_sel_hi:[1,0]
	v_pk_mul_f32 v[88:89], v[82:83], v[98:99] op_sel_hi:[1,0]
	v_pk_mul_f32 v[82:83], v[80:81], v[98:99] op_sel_hi:[1,0]
	v_cvt_pk_bf16_f32 v80, v84, v85
	v_cvt_pk_bf16_f32 v81, v86, v87
	v_cvt_pk_bf16_f32 v82, v82, v83
	v_cvt_pk_bf16_f32 v83, v88, v89
	global_store_dwordx4 v[92:93], v[80:83], off offset:256
	s_nop 1
	v_or_b32_e32 v80, 48, v142
	v_ashrrev_i32_e32 v81, 31, v80
	v_lshlrev_b64 v[80:81], 12, v[80:81]
	s_waitcnt vmcnt(10)
; DI float ss_get(const ssacc_t* p) { const ssacc_t v = *p; return (float)(unsigned)(v >> 32) + (float)(unsigned)(v & 0xffffffffull) * 2.3283064365386963e-10f; }
; DI u32x4 pack8(const f32x4& a, const f32x4& b) { u32x4 w; w.x = cvtpk(a[0], a[1]); w.y = cvtpk(a[2], a[3]); w.z = cvtpk(b[0], b[1]); w.w = cvtpk(b[2], b[3]); return w; }
;     DI const bf16_t* KV() const { return (const bf16_t*)(ws + WS_KV); }
;     DI void operator()(const Acc& acc, const Unit& u, int wr, int wc, int fr, int fq) const {
;     ...
;             for (int m = 0; m < 4; ++m) {
;                 asm volatile("" ::: "memory");
;                 const int row = u.pm * 256 + ai * 128 + wr * 64 + m * 16 + fr;
;                 const float rs = rsqrtf(ss_get(sskv + row) * (1.f / 256.f) + EPS_);
; #pragma unroll
;                 for (int bj = 0; bj < 2; ++bj) {
;                     const f32x4 v0 = acc[ai][bj][m][0] * rs, v1 = acc[ai][bj][m][1] * rs;
;                     const int c0 = u.pn * 256 + bj * 128 + wc * 32 + 8 * fq;
;                     *(u32x4*)(KV + (size_t)row * 2048 + c0) = pack8(v0, v1);
;                 }
	v_mov_b32_e32 v82, v218
	v_mov_b32_e32 v83, v219
	v_mov_b32_e32 v128, v83
	v_lshlrev_b64 v[84:85], s14, v[128:129]
	v_min_u32_e32 v83, 1, v84
	v_or_b32_e32 v83, v85, v83
	v_cvt_f32_u32_e32 v83, v83
	v_cvt_f32_u32_e32 v82, v82
	v_ldexp_f32 v83, v83, s15
	v_fmac_f32_e32 v83, 0x2f800000, v82
	v_fmamk_f32 v82, v83, 0x3b800000, v195
	v_cmp_gt_f32_e32 vcc, s27, v82
	v_mul_f32_e32 v83, 0x4b800000, v82
	s_nop 0
	v_cndmask_b32_e32 v82, v82, v83, vcc
	v_rsq_f32_e32 v82, v82
	s_nop 0
	v_mul_f32_e32 v83, 0x45800000, v82
	v_cndmask_b32_e32 v82, v82, v83, vcc
	v_pk_mul_f32 v[76:77], v[76:77], v[82:83] op_sel_hi:[1,0]
	v_pk_mul_f32 v[78:79], v[78:79], v[82:83] op_sel_hi:[1,0]
	v_pk_mul_f32 v[84:85], v[74:75], v[82:83] op_sel_hi:[1,0]
	v_pk_mul_f32 v[74:75], v[72:73], v[82:83] op_sel_hi:[1,0]
	v_cvt_pk_bf16_f32 v72, v76, v77
	v_lshl_add_u64 v[76:77], s[48:49], 0, v[80:81]
	v_cvt_pk_bf16_f32 v73, v78, v79
	v_cvt_pk_bf16_f32 v74, v74, v75
	v_cvt_pk_bf16_f32 v75, v84, v85
	v_lshl_add_u64 v[76:77], v[76:77], 0, v[120:121]
	global_store_dwordx4 v[76:77], v[72:75], off
	v_pk_mul_f32 v[70:71], v[70:71], v[82:83] op_sel_hi:[1,0]
	v_pk_mul_f32 v[68:69], v[68:69], v[82:83] op_sel_hi:[1,0]
	v_pk_mul_f32 v[72:73], v[66:67], v[82:83] op_sel_hi:[1,0]
	v_pk_mul_f32 v[66:67], v[64:65], v[82:83] op_sel_hi:[1,0]
	v_cvt_pk_bf16_f32 v64, v68, v69
	v_cvt_pk_bf16_f32 v65, v70, v71
	v_cvt_pk_bf16_f32 v66, v66, v67
	v_cvt_pk_bf16_f32 v67, v72, v73
	global_store_dwordx4 v[76:77], v[64:67], off offset:256
	s_nop 1
	v_add_u32_e32 v64, 0x80, v142
	v_ashrrev_i32_e32 v65, 31, v64
	v_lshlrev_b64 v[64:65], 12, v[64:65]
	s_waitcnt vmcnt(11)
	v_mov_b32_e32 v66, v220
	v_mov_b32_e32 v67, v221
	v_mov_b32_e32 v128, v67
	v_lshlrev_b64 v[68:69], s14, v[128:129]
	v_min_u32_e32 v67, 1, v68
	v_or_b32_e32 v67, v69, v67
	v_cvt_f32_u32_e32 v67, v67
	v_cvt_f32_u32_e32 v66, v66
	v_ldexp_f32 v67, v67, s15
	v_fmac_f32_e32 v67, 0x2f800000, v66
	v_fmamk_f32 v66, v67, 0x3b800000, v195
	v_cmp_gt_f32_e32 vcc, s27, v66
	v_mul_f32_e32 v67, 0x4b800000, v66
	s_nop 0
	v_cndmask_b32_e32 v66, v66, v67, vcc
	v_rsq_f32_e32 v66, v66
	s_nop 0
	v_mul_f32_e32 v67, 0x45800000, v66
	v_cndmask_b32_e32 v66, v66, v67, vcc
	v_pk_mul_f32 v[60:61], v[60:61], v[66:67] op_sel_hi:[1,0]
	v_pk_mul_f32 v[62:63], v[62:63], v[66:67] op_sel_hi:[1,0]
	v_pk_mul_f32 v[68:69], v[58:59], v[66:67] op_sel_hi:[1,0]
	v_pk_mul_f32 v[58:59], v[56:57], v[66:67] op_sel_hi:[1,0]
	v_cvt_pk_bf16_f32 v56, v60, v61
	v_lshl_add_u64 v[60:61], s[48:49], 0, v[64:65]
	v_cvt_pk_bf16_f32 v57, v62, v63
	v_cvt_pk_bf16_f32 v58, v58, v59
	v_cvt_pk_bf16_f32 v59, v68, v69
	v_lshl_add_u64 v[60:61], v[60:61], 0, v[120:121]
	global_store_dwordx4 v[60:61], v[56:59], off
	v_pk_mul_f32 v[54:55], v[54:55], v[66:67] op_sel_hi:[1,0]
	v_pk_mul_f32 v[52:53], v[52:53], v[66:67] op_sel_hi:[1,0]
	v_pk_mul_f32 v[56:57], v[50:51], v[66:67] op_sel_hi:[1,0]
	v_pk_mul_f32 v[50:51], v[48:49], v[66:67] op_sel_hi:[1,0]
	v_cvt_pk_bf16_f32 v48, v52, v53
	v_cvt_pk_bf16_f32 v49, v54, v55
	v_cvt_pk_bf16_f32 v50, v50, v51
	v_cvt_pk_bf16_f32 v51, v56, v57
	global_store_dwordx4 v[60:61], v[48:51], off offset:256
	s_nop 1
	v_add_u32_e32 v48, 0x90, v142
	v_ashrrev_i32_e32 v49, 31, v48
	v_lshlrev_b64 v[48:49], 12, v[48:49]
	s_waitcnt vmcnt(12)
; DI float ss_get(const ssacc_t* p) { const ssacc_t v = *p; return (float)(unsigned)(v >> 32) + (float)(unsigned)(v & 0xffffffffull) * 2.3283064365386963e-10f; }
; #define PG8_BAR __builtin_amdgcn_s_barrier()
; DI u32x4 pack8(const f32x4& a, const f32x4& b) { u32x4 w; w.x = cvtpk(a[0], a[1]); w.y = cvtpk(a[2], a[3]); w.z = cvtpk(b[0], b[1]); w.w = cvtpk(b[2], b[3]); return w; }
;     DI const bf16_t* KV() const { return (const bf16_t*)(ws + WS_KV); }
; template <class Epi, class Sched, bool ALIGN_EPI, bool SP2>
; __device__ __forceinline__ void gemm_phase(LAS unsigned char* lds, const Gemm g, const Sched& S, const Epi& E) {
;     ...
;         if constexpr (ALIGN_EPI) { if (wr == 0) PG8_BAR; }
;         E(acc, cur, wr, wc, fr, fq);
;         if (!has_next) break;
; #pragma unroll
;         for (int a = 0; a < 2; ++a)
; #pragma unroll
;             for (int b = 0; b < 2; ++b)
; #pragma unroll
;                 for (int m = 0; m < 4; ++m)
; #pragma unroll
;                     for (int n = 0; n < 2; ++n) acc[a][b][m][n] = (f32x4){0.f, 0.f, 0.f, 0.f};
;         cur = nxt; cA = nA; cB = nB; ++ui;
;         if constexpr (ALIGN_EPI) { if (wr == 1) PG8_BAR; }
;     }
;     DI void operator()(const Acc& acc, const Unit& u, int wr, int wc, int fr, int fq) const {
;     ...
;             for (int m = 0; m < 4; ++m) {
;                 asm volatile("" ::: "memory");
;                 const int row = u.pm * 256 + ai * 128 + wr * 64 + m * 16 + fr;
;                 const float rs = rsqrtf(ss_get(sskv + row) * (1.f / 256.f) + EPS_);
; #pragma unroll
;                 for (int bj = 0; bj < 2; ++bj) {
;                     const f32x4 v0 = acc[ai][bj][m][0] * rs, v1 = acc[ai][bj][m][1] * rs;
;                     const int c0 = u.pn * 256 + bj * 128 + wc * 32 + 8 * fq;
;                     *(u32x4*)(KV + (size_t)row * 2048 + c0) = pack8(v0, v1);
;                 }
	v_mov_b32_e32 v50, v222
	v_mov_b32_e32 v51, v223
	v_mov_b32_e32 v128, v51
	v_lshlrev_b64 v[52:53], s14, v[128:129]
	v_min_u32_e32 v51, 1, v52
	v_or_b32_e32 v51, v53, v51
	v_cvt_f32_u32_e32 v51, v51
	v_cvt_f32_u32_e32 v50, v50
	v_ldexp_f32 v51, v51, s15
	v_fmac_f32_e32 v51, 0x2f800000, v50
	v_fmamk_f32 v50, v51, 0x3b800000, v195
	v_cmp_gt_f32_e32 vcc, s27, v50
	v_mul_f32_e32 v51, 0x4b800000, v50
	s_nop 0
	v_cndmask_b32_e32 v50, v50, v51, vcc
	v_rsq_f32_e32 v50, v50
	s_nop 0
	v_mul_f32_e32 v51, 0x45800000, v50
	v_cndmask_b32_e32 v50, v50, v51, vcc
	v_pk_mul_f32 v[44:45], v[44:45], v[50:51] op_sel_hi:[1,0]
	v_pk_mul_f32 v[46:47], v[46:47], v[50:51] op_sel_hi:[1,0]
	v_pk_mul_f32 v[52:53], v[42:43], v[50:51] op_sel_hi:[1,0]
	v_pk_mul_f32 v[42:43], v[40:41], v[50:51] op_sel_hi:[1,0]
	v_cvt_pk_bf16_f32 v40, v44, v45
	v_lshl_add_u64 v[44:45], s[48:49], 0, v[48:49]
	v_cvt_pk_bf16_f32 v41, v46, v47
	v_cvt_pk_bf16_f32 v42, v42, v43
	v_cvt_pk_bf16_f32 v43, v52, v53
	v_lshl_add_u64 v[44:45], v[44:45], 0, v[120:121]
	global_store_dwordx4 v[44:45], v[40:43], off
	v_pk_mul_f32 v[38:39], v[38:39], v[50:51] op_sel_hi:[1,0]
	v_pk_mul_f32 v[36:37], v[36:37], v[50:51] op_sel_hi:[1,0]
	v_pk_mul_f32 v[40:41], v[34:35], v[50:51] op_sel_hi:[1,0]
	v_pk_mul_f32 v[34:35], v[32:33], v[50:51] op_sel_hi:[1,0]
	v_cvt_pk_bf16_f32 v32, v36, v37
	v_cvt_pk_bf16_f32 v33, v38, v39
	v_cvt_pk_bf16_f32 v34, v34, v35
	v_cvt_pk_bf16_f32 v35, v40, v41
	global_store_dwordx4 v[44:45], v[32:35], off offset:256
	s_nop 1
	v_add_u32_e32 v32, 0xa0, v142
	v_ashrrev_i32_e32 v33, 31, v32
	v_lshlrev_b64 v[32:33], 12, v[32:33]
	s_waitcnt vmcnt(13)
	v_mov_b32_e32 v34, v224
	v_mov_b32_e32 v35, v225
	v_mov_b32_e32 v128, v35
	v_lshlrev_b64 v[36:37], s14, v[128:129]
	v_min_u32_e32 v35, 1, v36
	v_or_b32_e32 v35, v37, v35
	v_cvt_f32_u32_e32 v35, v35
	v_cvt_f32_u32_e32 v34, v34
	v_ldexp_f32 v35, v35, s15
	v_fmac_f32_e32 v35, 0x2f800000, v34
	v_fmamk_f32 v34, v35, 0x3b800000, v195
	v_cmp_gt_f32_e32 vcc, s27, v34
	v_mul_f32_e32 v35, 0x4b800000, v34
	s_nop 0
	v_cndmask_b32_e32 v34, v34, v35, vcc
	v_rsq_f32_e32 v34, v34
	s_nop 0
	v_mul_f32_e32 v35, 0x45800000, v34
	v_cndmask_b32_e32 v34, v34, v35, vcc
	v_pk_mul_f32 v[28:29], v[28:29], v[34:35] op_sel_hi:[1,0]
	v_pk_mul_f32 v[30:31], v[30:31], v[34:35] op_sel_hi:[1,0]
	v_pk_mul_f32 v[36:37], v[26:27], v[34:35] op_sel_hi:[1,0]
	v_pk_mul_f32 v[26:27], v[24:25], v[34:35] op_sel_hi:[1,0]
	v_cvt_pk_bf16_f32 v24, v28, v29
	v_lshl_add_u64 v[28:29], s[48:49], 0, v[32:33]
	v_cvt_pk_bf16_f32 v25, v30, v31
	v_cvt_pk_bf16_f32 v26, v26, v27
	v_cvt_pk_bf16_f32 v27, v36, v37
	v_lshl_add_u64 v[28:29], v[28:29], 0, v[120:121]
	global_store_dwordx4 v[28:29], v[24:27], off
	v_pk_mul_f32 v[22:23], v[22:23], v[34:35] op_sel_hi:[1,0]
	v_pk_mul_f32 v[20:21], v[20:21], v[34:35] op_sel_hi:[1,0]
	v_pk_mul_f32 v[24:25], v[18:19], v[34:35] op_sel_hi:[1,0]
	v_pk_mul_f32 v[18:19], v[16:17], v[34:35] op_sel_hi:[1,0]
	v_cvt_pk_bf16_f32 v16, v20, v21
	v_cvt_pk_bf16_f32 v17, v22, v23
	v_cvt_pk_bf16_f32 v18, v18, v19
	v_cvt_pk_bf16_f32 v19, v24, v25
	global_store_dwordx4 v[28:29], v[16:19], off offset:256
	s_nop 1
	v_add_u32_e32 v16, 0xb0, v142
	v_ashrrev_i32_e32 v17, 31, v16
	v_lshlrev_b64 v[16:17], 12, v[16:17]
	s_waitcnt vmcnt(14)
	v_mov_b32_e32 v18, v226
	v_mov_b32_e32 v19, v227
	v_mov_b32_e32 v128, v19
	v_lshlrev_b64 v[20:21], s14, v[128:129]
	v_min_u32_e32 v19, 1, v20
	v_or_b32_e32 v19, v21, v19
	v_cvt_f32_u32_e32 v19, v19
	v_cvt_f32_u32_e32 v18, v18
	v_ldexp_f32 v19, v19, s15
	v_fmac_f32_e32 v19, 0x2f800000, v18
	v_fmamk_f32 v18, v19, 0x3b800000, v195
	v_cmp_gt_f32_e32 vcc, s27, v18
	v_mul_f32_e32 v19, 0x4b800000, v18
	s_mov_b64 s[14:15], -1
	v_cndmask_b32_e32 v18, v18, v19, vcc
	v_rsq_f32_e32 v18, v18
	s_nop 0
	v_mul_f32_e32 v19, 0x45800000, v18
	v_cndmask_b32_e32 v18, v18, v19, vcc
	v_pk_mul_f32 v[12:13], v[12:13], v[18:19] op_sel_hi:[1,0]
	v_pk_mul_f32 v[14:15], v[14:15], v[18:19] op_sel_hi:[1,0]
	v_pk_mul_f32 v[20:21], v[10:11], v[18:19] op_sel_hi:[1,0]
	v_pk_mul_f32 v[10:11], v[8:9], v[18:19] op_sel_hi:[1,0]
	v_cvt_pk_bf16_f32 v8, v12, v13
	v_lshl_add_u64 v[12:13], s[48:49], 0, v[16:17]
	v_cvt_pk_bf16_f32 v9, v14, v15
	v_cvt_pk_bf16_f32 v10, v10, v11
	v_cvt_pk_bf16_f32 v11, v20, v21
	v_lshl_add_u64 v[12:13], v[12:13], 0, v[120:121]
	global_store_dwordx4 v[12:13], v[8:11], off
	v_pk_mul_f32 v[6:7], v[6:7], v[18:19] op_sel_hi:[1,0]
	v_pk_mul_f32 v[4:5], v[4:5], v[18:19] op_sel_hi:[1,0]
	v_pk_mul_f32 v[8:9], v[2:3], v[18:19] op_sel_hi:[1,0]
	v_pk_mul_f32 v[2:3], v[0:1], v[18:19] op_sel_hi:[1,0]
	v_cvt_pk_bf16_f32 v0, v4, v5
	v_cvt_pk_bf16_f32 v1, v6, v7
	v_cvt_pk_bf16_f32 v2, v2, v3
	v_cvt_pk_bf16_f32 v3, v8, v9
	s_and_b64 vcc, exec, s[46:47]
	global_store_dwordx4 v[12:13], v[0:3], off offset:256
	s_cbranch_vccnz .LBB0_849
	s_andn2_b64 vcc, exec, s[42:43]
	s_cbranch_vccnz .LBB0_848
	s_barrier
	s_branch .LBB0_848

; #define LAS __attribute__((address_space(3)))
; DI int crow(int i, int h) { return (i & 3) + 8 * (i >> 2) + 4 * h; }
; #define MFMA32(a, b, c) __builtin_amdgcn_mfma_f32_32x32x16_bf16((a), (b), (c), 0, 0, 0)
; template <bool ATOM>
; DI void mla_unit(LAS unsigned char* lds, const AttnPtrs& P, int b, int hd, int qb) {
;     ...
;         if (keyb <= qb * 128 + rg * 32 + 31) {
;             const LAS unsigned char* Kw = lds + (t & 1) * BUFB + kwo;
;             const LAS unsigned char* Vw = lds + (t & 1) * BUFB + vwo;
;             f32x16 xa, xb;
; #pragma unroll
;             for (int i = 0; i < 16; ++i) { xa[i] = 0.f; xb[i] = 0.f; }
; #pragma unroll
;             for (int kk = 0; kk < NKK; kk += 2) {
;                 const bf16x8 a0 = *(const LAS bf16x8*)(Kw + kk * 32), a1 = *(const LAS bf16x8*)(Kw + kk * 32 + 32);
;                 xa = MFMA32(a0, qf[kk], xa); xb = MFMA32(a1, qf[kk + 1], xb);
;                 if ((kk & 3) == 2) __builtin_amdgcn_sched_barrier(0);
;             }
;             f32x16 x0;
; #pragma unroll
;             for (int i = 0; i < 16; ++i) x0[i] = xa[i] + xb[i];
;             if (keyb + 31 > qb * 128 + rg * 32) {
; #pragma unroll
;                 for (int i = 0; i < 16; ++i) if (keyb + crow(i, h) > fq_) x0[i] = -INFINITY;
;             }
.LBB0_1051:
	s_add_i32 s40, s35, s14
	s_cmp_gt_i32 s40, s36
	s_cbranch_scc1 .LBB0_1057
	s_bitcmp1_b32 s4, 0
	s_cselect_b32 s4, 0xac00, 0
	s_add_i32 s4, s4, 0
	v_add3_u32 v125, s4, v215, v128
	ds_read_b128 v[0:3], v125
	ds_read_b128 v[80:83], v125 offset:32
	ds_read_b128 v[216:219], v125 offset:64
	s_waitcnt lgkmcnt(2)
	v_mfma_f32_32x32x16_bf16 v[0:15], v[0:3], v[180:183], 0
	s_waitcnt lgkmcnt(0)
	v_mfma_f32_32x32x16_bf16 v[0:15], v[216:219], v[172:175], v[0:15]
	ds_read_b128 v[216:219], v125 offset:96
	v_mfma_f32_32x32x16_bf16 v[80:95], v[80:83], v[176:179], 0
	s_waitcnt lgkmcnt(0)
	v_mfma_f32_32x32x16_bf16 v[80:95], v[216:219], v[168:171], v[80:95]
	ds_read_b128 v[216:219], v125 offset:128
	s_waitcnt lgkmcnt(0)
	v_mfma_f32_32x32x16_bf16 v[0:15], v[216:219], v[164:167], v[0:15]
	ds_read_b128 v[216:219], v125 offset:160
	s_waitcnt lgkmcnt(0)
	v_mfma_f32_32x32x16_bf16 v[80:95], v[216:219], v[160:163], v[80:95]
	ds_read_b128 v[216:219], v125 offset:192
	s_waitcnt lgkmcnt(0)
	v_mfma_f32_32x32x16_bf16 v[0:15], v[216:219], v[156:159], v[0:15]
	ds_read_b128 v[216:219], v125 offset:224
	s_waitcnt lgkmcnt(0)
	v_mfma_f32_32x32x16_bf16 v[80:95], v[216:219], v[152:155], v[80:95]
	ds_read_b128 v[216:219], v125 offset:256
	s_waitcnt lgkmcnt(0)
	v_mfma_f32_32x32x16_bf16 v[0:15], v[216:219], v[148:151], v[0:15]
	ds_read_b128 v[216:219], v125 offset:288
	s_waitcnt lgkmcnt(0)
	v_mfma_f32_32x32x16_bf16 v[80:95], v[216:219], v[144:147], v[80:95]
	ds_read_b128 v[216:219], v125 offset:320
	s_waitcnt lgkmcnt(0)
	v_mfma_f32_32x32x16_bf16 v[0:15], v[216:219], v[140:143], v[0:15]
	ds_read_b128 v[216:219], v125 offset:352
	s_waitcnt lgkmcnt(0)
	v_mfma_f32_32x32x16_bf16 v[80:95], v[216:219], v[136:139], v[80:95]
	s_add_i32 s40, s40, 31
	s_nop 10
	v_pk_add_f32 v[14:15], v[14:15], v[94:95]
	v_pk_add_f32 v[12:13], v[12:13], v[92:93]
	v_pk_add_f32 v[10:11], v[10:11], v[90:91]
	v_pk_add_f32 v[8:9], v[8:9], v[88:89]
	v_pk_add_f32 v[6:7], v[6:7], v[86:87]
	v_pk_add_f32 v[4:5], v[4:5], v[84:85]
	v_pk_add_f32 v[2:3], v[2:3], v[82:83]
	s_cmp_le_i32 s40, s34
	v_pk_add_f32 v[80:81], v[0:1], v[80:81]
	s_cbranch_scc1 .LBB0_1054
	v_add_u32_e32 v0, s14, v123
	v_cmp_lt_i32_e32 vcc, v0, v214
	v_add_u32_e32 v1, 2, v0
	s_nop 0
	v_cndmask_b32_e32 v81, v205, v81, vcc
	v_cmp_le_i32_e32 vcc, v0, v214
	s_nop 1
	v_cndmask_b32_e32 v80, v205, v80, vcc
	v_cmp_le_i32_e32 vcc, v1, v214
	v_add_u32_e32 v1, 3, v0
	s_nop 0
	v_cndmask_b32_e32 v2, v205, v2, vcc
	v_cmp_le_i32_e32 vcc, v1, v214
	v_add_u32_e32 v1, 8, v0
	s_nop 0
	v_cndmask_b32_e32 v3, v205, v3, vcc
	v_cmp_le_i32_e32 vcc, v1, v214
	v_add_u32_e32 v1, 9, v0
	s_nop 0
	v_cndmask_b32_e32 v4, v205, v4, vcc
	v_cmp_le_i32_e32 vcc, v1, v214
	v_add_u32_e32 v1, 10, v0
	s_nop 0
	v_cndmask_b32_e32 v5, v205, v5, vcc
	v_cmp_le_i32_e32 vcc, v1, v214
	v_add_u32_e32 v1, 11, v0
	s_nop 0
	v_cndmask_b32_e32 v6, v205, v6, vcc
	v_cmp_le_i32_e32 vcc, v1, v214
	v_add_u32_e32 v1, 16, v0
	s_nop 0
	v_cndmask_b32_e32 v7, v205, v7, vcc
	v_cmp_le_i32_e32 vcc, v1, v214
	v_add_u32_e32 v1, 17, v0
	s_nop 0
	v_cndmask_b32_e32 v8, v205, v8, vcc
	v_cmp_le_i32_e32 vcc, v1, v214
	v_add_u32_e32 v1, 18, v0
	s_nop 0
	v_cndmask_b32_e32 v9, v205, v9, vcc
	v_cmp_le_i32_e32 vcc, v1, v214
	v_add_u32_e32 v1, 19, v0
	s_nop 0
	v_cndmask_b32_e32 v10, v205, v10, vcc
	v_cmp_le_i32_e32 vcc, v1, v214
	v_add_u32_e32 v1, 24, v0
	s_nop 0
	v_cndmask_b32_e32 v11, v205, v11, vcc
	v_cmp_le_i32_e32 vcc, v1, v214
	v_add_u32_e32 v1, 25, v0
	s_nop 0
	v_cndmask_b32_e32 v12, v205, v12, vcc
	v_cmp_le_i32_e32 vcc, v1, v214
	v_add_u32_e32 v1, 26, v0
	v_add_u32_e32 v0, 27, v0
	v_cndmask_b32_e32 v13, v205, v13, vcc
	v_cmp_le_i32_e32 vcc, v1, v214
	s_nop 1
	v_cndmask_b32_e32 v14, v205, v14, vcc
	v_cmp_le_i32_e32 vcc, v0, v214
	s_nop 1
	v_cndmask_b32_e32 v15, v205, v15, vcc

; DI float fexp2(float x) { return __builtin_amdgcn_exp2f(x); }
; DI s16x4 vtr(const LAS unsigned char* p) { return __builtin_bit_cast(s16x4, __builtin_amdgcn_ds_read_tr16_b64_v4i16((LAS v4i16_t*)p)); }
; #define MFMA32(a, b, c) __builtin_amdgcn_mfma_f32_32x32x16_bf16((a), (b), (c), 0, 0, 0)
; template <bool ATOM>
; DI void mla_unit(LAS unsigned char* lds, const AttnPtrs& P, int b, int hd, int qb) {
;     ...
;             float psum = 0.f;
; #pragma unroll
;             for (int i = 0; i < 16; ++i) { x0[i] = fexp2(x0[i] - msafe); psum += x0[i]; }
;             lrun = lrun * alpha + psum; mrun = mnew;
;             if (__builtin_amdgcn_ballot_w64(alpha != 1.f) != 0ull) {
; #pragma unroll
;                 for (int d = 0; d < NDV; ++d)
; #pragma unroll
;                     for (int i = 0; i < 16; ++i) o[d][i] *= alpha;
;             }
; #pragma unroll
;             for (int s2 = 0; s2 < 2; ++s2) {
;                 const bf16x8 pf = pack_step(x0, s2);
; #pragma unroll
;                 for (int d = 0; d < NDV; ++d) {
;                     const s16x4 lo = vtr(Vw + (16 * s2) * VSTR + d * 64), hi = vtr(Vw + (16 * s2 + 8) * VSTR + d * 64);
;                     const bf16x8 pa = __builtin_shufflevector(lo, hi, 0, 1, 2, 3, 4, 5, 6, 7);
;                     o[d] = MFMA32(pa, pf, o[d]);
;                 }
;                 __builtin_amdgcn_sched_barrier(0);
;             }
.LBB0_1056:
	v_sub_f32_e32 v80, v80, v1
	v_exp_f32_e32 v80, v80
	v_sub_f32_e32 v81, v81, v1
	v_exp_f32_e32 v81, v81
	v_sub_f32_e32 v2, v2, v1
	v_exp_f32_e32 v2, v2
	v_sub_f32_e32 v3, v3, v1
	v_exp_f32_e32 v3, v3
	v_sub_f32_e32 v4, v4, v1
	v_add_f32_e32 v82, 0, v80
	v_exp_f32_e32 v4, v4
	v_sub_f32_e32 v5, v5, v1
	v_add_f32_e32 v82, v81, v82
	v_exp_f32_e32 v5, v5
	v_sub_f32_e32 v6, v6, v1
	v_add_f32_e32 v82, v2, v82
	v_exp_f32_e32 v6, v6
	v_sub_f32_e32 v7, v7, v1
	v_add_f32_e32 v82, v3, v82
	v_exp_f32_e32 v7, v7
	v_sub_f32_e32 v8, v8, v1
	v_add_f32_e32 v82, v4, v82
	v_exp_f32_e32 v8, v8
	v_sub_f32_e32 v9, v9, v1
	v_add_f32_e32 v82, v5, v82
	v_exp_f32_e32 v9, v9
	v_sub_f32_e32 v10, v10, v1
	v_add_f32_e32 v82, v6, v82
	v_exp_f32_e32 v10, v10
	v_sub_f32_e32 v11, v11, v1
	v_add_f32_e32 v82, v7, v82
	v_exp_f32_e32 v11, v11
	v_sub_f32_e32 v12, v12, v1
	v_add_f32_e32 v82, v8, v82
	v_exp_f32_e32 v12, v12
	v_sub_f32_e32 v13, v13, v1
	v_add_f32_e32 v82, v9, v82
	v_exp_f32_e32 v13, v13
	v_sub_f32_e32 v14, v14, v1
	v_add_f32_e32 v82, v10, v82
	v_exp_f32_e32 v14, v14
	v_sub_f32_e32 v1, v15, v1
	v_add_f32_e32 v82, v11, v82
	v_exp_f32_e32 v15, v1
	v_add_f32_e32 v82, v12, v82
	v_add_f32_e32 v82, v13, v82
	v_add_f32_e32 v82, v14, v82
	v_add_f32_e32 v82, v15, v82
	v_fmac_f32_e32 v82, v213, v0
	v_cvt_pk_bf16_f32 v0, v80, v81
	v_add3_u32 v80, s4, v210, v211
	v_cvt_pk_bf16_f32 v1, v2, v3
	v_cvt_pk_bf16_f32 v2, v4, v5
	v_cvt_pk_bf16_f32 v3, v6, v7
	ds_read_b64_tr_b16 v[4:5], v80 offset:25600
	ds_read_b64_tr_b16 v[6:7], v80 offset:27904
	s_waitcnt lgkmcnt(0)
	v_mfma_f32_32x32x16_bf16 v[64:79], v[4:7], v[0:3], v[64:79]
	ds_read_b64_tr_b16 v[4:5], v80 offset:25664
	ds_read_b64_tr_b16 v[6:7], v80 offset:27968
	s_waitcnt lgkmcnt(0)
	v_mfma_f32_32x32x16_bf16 v[48:63], v[4:7], v[0:3], v[48:63]
	ds_read_b64_tr_b16 v[4:5], v80 offset:25728
	ds_read_b64_tr_b16 v[6:7], v80 offset:28032
	s_waitcnt lgkmcnt(0)
	v_mfma_f32_32x32x16_bf16 v[32:47], v[4:7], v[0:3], v[32:47]
	ds_read_b64_tr_b16 v[4:5], v80 offset:25792
	ds_read_b64_tr_b16 v[6:7], v80 offset:28096
	s_waitcnt lgkmcnt(0)
	v_mfma_f32_32x32x16_bf16 v[16:31], v[4:7], v[0:3], v[16:31]
	ds_read_b64_tr_b16 v[4:5], v80 offset:30208
	ds_read_b64_tr_b16 v[6:7], v80 offset:32512
	v_cvt_pk_bf16_f32 v0, v8, v9
	v_cvt_pk_bf16_f32 v1, v10, v11
	v_cvt_pk_bf16_f32 v2, v12, v13
	v_cvt_pk_bf16_f32 v3, v14, v15
	s_waitcnt lgkmcnt(0)
	s_nop 0
	v_mfma_f32_32x32x16_bf16 v[64:79], v[4:7], v[0:3], v[64:79]
	ds_read_b64_tr_b16 v[4:5], v80 offset:30272
	ds_read_b64_tr_b16 v[6:7], v80 offset:32576
	s_waitcnt lgkmcnt(0)
	v_mfma_f32_32x32x16_bf16 v[48:63], v[4:7], v[0:3], v[48:63]
	ds_read_b64_tr_b16 v[4:5], v80 offset:30336
	ds_read_b64_tr_b16 v[6:7], v80 offset:32640
	s_waitcnt lgkmcnt(0)
	v_mfma_f32_32x32x16_bf16 v[32:47], v[4:7], v[0:3], v[32:47]
	ds_read_b64_tr_b16 v[4:5], v80 offset:30400
	ds_read_b64_tr_b16 v[6:7], v80 offset:32704
	s_waitcnt lgkmcnt(0)
	v_mfma_f32_32x32x16_bf16 v[16:31], v[4:7], v[0:3], v[16:31]
	v_mov_b32_e32 v213, v82
	s_branch .LBB0_1058

; #define LAS __attribute__((address_space(3)))
; DI int crow(int i, int h) { return (i & 3) + 8 * (i >> 2) + 4 * h; }
; #define MFMA32(a, b, c) __builtin_amdgcn_mfma_f32_32x32x16_bf16((a), (b), (c), 0, 0, 0)
; template <bool ATOM>
; DI void mla_unit(LAS unsigned char* lds, const AttnPtrs& P, int b, int hd, int qb) {
;     ...
;         if (keyb <= qb * 128 + rg * 32 + 31) {
;             const LAS unsigned char* Kw = lds + (t & 1) * BUFB + kwo;
;             const LAS unsigned char* Vw = lds + (t & 1) * BUFB + vwo;
;             f32x16 xa, xb;
; #pragma unroll
;             for (int i = 0; i < 16; ++i) { xa[i] = 0.f; xb[i] = 0.f; }
; #pragma unroll
;             for (int kk = 0; kk < NKK; kk += 2) {
;                 const bf16x8 a0 = *(const LAS bf16x8*)(Kw + kk * 32), a1 = *(const LAS bf16x8*)(Kw + kk * 32 + 32);
;                 xa = MFMA32(a0, qf[kk], xa); xb = MFMA32(a1, qf[kk + 1], xb);
;                 if ((kk & 3) == 2) __builtin_amdgcn_sched_barrier(0);
;             }
;             f32x16 x0;
; #pragma unroll
;             for (int i = 0; i < 16; ++i) x0[i] = xa[i] + xb[i];
;             if (keyb + 31 > qb * 128 + rg * 32) {
; #pragma unroll
;                 for (int i = 0; i < 16; ++i) if (keyb + crow(i, h) > fq_) x0[i] = -INFINITY;
;             }
.LBB0_1077:
	s_add_i32 s37, s23, s14
	s_cmp_gt_i32 s37, s34
	s_cbranch_scc1 .LBB0_1083
	s_bitcmp1_b32 s4, 0
	s_cselect_b32 s4, 0xac00, 0
	s_add_i32 s4, s4, 0
	v_add3_u32 v125, s4, v215, v128
	ds_read_b128 v[0:3], v125
	ds_read_b128 v[80:83], v125 offset:32
	ds_read_b128 v[216:219], v125 offset:64
	s_waitcnt lgkmcnt(2)
	v_mfma_f32_32x32x16_bf16 v[0:15], v[0:3], v[180:183], 0
	s_waitcnt lgkmcnt(0)
	v_mfma_f32_32x32x16_bf16 v[0:15], v[216:219], v[172:175], v[0:15]
	ds_read_b128 v[216:219], v125 offset:96
	v_mfma_f32_32x32x16_bf16 v[80:95], v[80:83], v[176:179], 0
	s_waitcnt lgkmcnt(0)
	v_mfma_f32_32x32x16_bf16 v[80:95], v[216:219], v[168:171], v[80:95]
	ds_read_b128 v[216:219], v125 offset:128
	s_waitcnt lgkmcnt(0)
	v_mfma_f32_32x32x16_bf16 v[0:15], v[216:219], v[164:167], v[0:15]
	ds_read_b128 v[216:219], v125 offset:160
	s_waitcnt lgkmcnt(0)
	v_mfma_f32_32x32x16_bf16 v[80:95], v[216:219], v[160:163], v[80:95]
	ds_read_b128 v[216:219], v125 offset:192
	s_waitcnt lgkmcnt(0)
	v_mfma_f32_32x32x16_bf16 v[0:15], v[216:219], v[156:159], v[0:15]
	ds_read_b128 v[216:219], v125 offset:224
	s_waitcnt lgkmcnt(0)
	v_mfma_f32_32x32x16_bf16 v[80:95], v[216:219], v[152:155], v[80:95]
	ds_read_b128 v[216:219], v125 offset:256
	s_waitcnt lgkmcnt(0)
	v_mfma_f32_32x32x16_bf16 v[0:15], v[216:219], v[148:151], v[0:15]
	ds_read_b128 v[216:219], v125 offset:288
	s_waitcnt lgkmcnt(0)
	v_mfma_f32_32x32x16_bf16 v[80:95], v[216:219], v[144:147], v[80:95]
	ds_read_b128 v[216:219], v125 offset:320
	s_waitcnt lgkmcnt(0)
	v_mfma_f32_32x32x16_bf16 v[0:15], v[216:219], v[140:143], v[0:15]
	ds_read_b128 v[216:219], v125 offset:352
	s_waitcnt lgkmcnt(0)
	v_mfma_f32_32x32x16_bf16 v[80:95], v[216:219], v[136:139], v[80:95]
	s_add_i32 s37, s37, 31
	s_nop 10
	v_pk_add_f32 v[14:15], v[14:15], v[94:95]
	v_pk_add_f32 v[12:13], v[12:13], v[92:93]
	v_pk_add_f32 v[10:11], v[10:11], v[90:91]
	v_pk_add_f32 v[8:9], v[8:9], v[88:89]
	v_pk_add_f32 v[6:7], v[6:7], v[86:87]
	v_pk_add_f32 v[4:5], v[4:5], v[84:85]
	v_pk_add_f32 v[2:3], v[2:3], v[82:83]
	s_cmp_le_i32 s37, s22
	v_pk_add_f32 v[80:81], v[0:1], v[80:81]
	s_cbranch_scc1 .LBB0_1080
	v_add_u32_e32 v0, s14, v123
	v_cmp_lt_i32_e32 vcc, v0, v214
	v_add_u32_e32 v1, 2, v0
	s_nop 0
	v_cndmask_b32_e32 v81, v205, v81, vcc
	v_cmp_le_i32_e32 vcc, v0, v214
	s_nop 1
	v_cndmask_b32_e32 v80, v205, v80, vcc
	v_cmp_le_i32_e32 vcc, v1, v214
	v_add_u32_e32 v1, 3, v0
	s_nop 0
	v_cndmask_b32_e32 v2, v205, v2, vcc
	v_cmp_le_i32_e32 vcc, v1, v214
	v_add_u32_e32 v1, 8, v0
	s_nop 0
	v_cndmask_b32_e32 v3, v205, v3, vcc
	v_cmp_le_i32_e32 vcc, v1, v214
	v_add_u32_e32 v1, 9, v0
	s_nop 0
	v_cndmask_b32_e32 v4, v205, v4, vcc
	v_cmp_le_i32_e32 vcc, v1, v214
	v_add_u32_e32 v1, 10, v0
	s_nop 0
	v_cndmask_b32_e32 v5, v205, v5, vcc
	v_cmp_le_i32_e32 vcc, v1, v214
	v_add_u32_e32 v1, 11, v0
	s_nop 0
	v_cndmask_b32_e32 v6, v205, v6, vcc
	v_cmp_le_i32_e32 vcc, v1, v214
	v_add_u32_e32 v1, 16, v0
	s_nop 0
	v_cndmask_b32_e32 v7, v205, v7, vcc
	v_cmp_le_i32_e32 vcc, v1, v214
	v_add_u32_e32 v1, 17, v0
	s_nop 0
	v_cndmask_b32_e32 v8, v205, v8, vcc
	v_cmp_le_i32_e32 vcc, v1, v214
	v_add_u32_e32 v1, 18, v0
	s_nop 0
	v_cndmask_b32_e32 v9, v205, v9, vcc
	v_cmp_le_i32_e32 vcc, v1, v214
	v_add_u32_e32 v1, 19, v0
	s_nop 0
	v_cndmask_b32_e32 v10, v205, v10, vcc
	v_cmp_le_i32_e32 vcc, v1, v214
	v_add_u32_e32 v1, 24, v0
	s_nop 0
	v_cndmask_b32_e32 v11, v205, v11, vcc
	v_cmp_le_i32_e32 vcc, v1, v214
	v_add_u32_e32 v1, 25, v0
	s_nop 0
	v_cndmask_b32_e32 v12, v205, v12, vcc
	v_cmp_le_i32_e32 vcc, v1, v214
	v_add_u32_e32 v1, 26, v0
	v_add_u32_e32 v0, 27, v0
	v_cndmask_b32_e32 v13, v205, v13, vcc
	v_cmp_le_i32_e32 vcc, v1, v214
	s_nop 1
	v_cndmask_b32_e32 v14, v205, v14, vcc
	v_cmp_le_i32_e32 vcc, v0, v214
	s_nop 1
	v_cndmask_b32_e32 v15, v205, v15, vcc

; DI float ss_get(const ssacc_t* p) { const ssacc_t v = *p; return (float)(unsigned)(v >> 32) + (float)(unsigned)(v & 0xffffffffull) * 2.3283064365386963e-10f; }
; DI unsigned cvtpk(float lo, float hi) { f32x2 v = {lo, hi}; bf16x2_t b = __builtin_convertvector(v, bf16x2_t); return __builtin_bit_cast(unsigned, b); }
; DI float fexp2(float x) { return __builtin_amdgcn_exp2f(x); }
; DI float sigmoidf_(float x) { return __builtin_amdgcn_rcpf(1.f + fexp2(-LOG2E * x)); }
;     DI void operator()(const Acc& acc, const Unit& u, int wr, int wc, int fr, int fq) const {
;     ...
;             for (int m = 0; m < 4; ++m) {
;                 asm volatile("" ::: "memory");
;                 const int row = u.pm * 256 + ai * 128 + wr * 64 + m * 16 + fr;
;                 const float rs = rsqrtf(ss_get(ssx1 + row) * (1.f / 2048.f) + EPS_);
; #pragma unroll
;                 for (int bj = 0; bj < 2; ++bj) {
;                     const f32x4 v0 = acc[ai][bj][m][0] * rs, v1 = acc[ai][bj][m][1] * rs;
;                     const int i0 = (u.pn * 256 + bj * 128 + wc * 32 + 8 * fq) >> 1;
;                     const float o0 = v0[0] * sigmoidf_(v0[0]) * v0[1], o1 = v0[2] * sigmoidf_(v0[2]) * v0[3];
;                     const float o2 = v1[0] * sigmoidf_(v1[0]) * v1[1], o3 = v1[2] * sigmoidf_(v1[2]) * v1[3];
;                     u32x2 w; w.x = cvtpk(o0, o1); w.y = cvtpk(o2, o3);
;                     *(u32x2*)(HM + (size_t)row * DFF_ + i0) = w;
;                 }
.LBB0_1368:
	v_lshl_add_u32 v142, s41, 8, v144
	v_ashrrev_i32_e32 v143, 31, v142
	v_lshl_add_u64 v[148:149], v[142:143], 3, s[44:45]
	global_load_dwordx2 v[212:213], v[148:149], off
	global_load_dwordx2 v[214:215], v[148:149], off offset:128
	global_load_dwordx2 v[216:217], v[148:149], off offset:256
	global_load_dwordx2 v[218:219], v[148:149], off offset:384
	global_load_dwordx2 v[220:221], v[148:149], off offset:1024
	global_load_dwordx2 v[222:223], v[148:149], off offset:1152
	global_load_dwordx2 v[224:225], v[148:149], off offset:1280
	global_load_dwordx2 v[226:227], v[148:149], off offset:1408
	s_min_u32 s14, s88, 32
	s_sub_i32 s15, 32, s14
	v_lshl_or_b32 v152, s40, 8, v146
	s_movk_i32 s4, 0x2c00
	s_waitcnt vmcnt(7)
	v_mov_b32_e32 v148, v212
	v_mov_b32_e32 v149, v213
	v_mov_b32_e32 v128, v149
	v_lshlrev_b64 v[150:151], s14, v[128:129]
	v_min_u32_e32 v128, 1, v150
	v_or_b32_e32 v128, v151, v128
	v_cvt_f32_u32_e32 v128, v128
	v_cvt_f32_u32_e32 v143, v148
	v_ldexp_f32 v128, v128, s15
	v_fmac_f32_e32 v128, 0x2f800000, v143
	v_fmamk_f32 v128, v128, 0x3a000000, v195
	v_cmp_gt_f32_e32 vcc, s27, v128
	v_mul_f32_e32 v143, 0x4b800000, v128
	s_nop 0
	v_cndmask_b32_e32 v128, v128, v143, vcc
	v_rsq_f32_e32 v128, v128
	s_nop 0
	v_mul_f32_e32 v143, 0x45800000, v128
	v_cndmask_b32_e32 v128, v128, v143, vcc
	v_pk_mul_f32 v[120:121], v[120:121], v[128:129] op_sel_hi:[1,0]
	v_pk_mul_f32 v[148:149], v[122:123], v[128:129] op_sel_hi:[1,0]
	v_mul_f32_e32 v123, 0xbfb8aa3b, v120
	v_exp_f32_e32 v123, v123
	v_pk_mul_f32 v[124:125], v[124:125], v[128:129] op_sel_hi:[1,0]
	v_ashrrev_i32_e32 v122, 1, v152
	v_mov_b32_e32 v152, v120
	v_add_f32_e32 v123, 1.0, v123
	v_rcp_f32_e32 v150, v123
	v_mul_f32_e32 v123, 0xbfb8aa3b, v148
	v_exp_f32_e32 v123, v123
	v_mov_b32_e32 v153, v148
	v_pk_mul_f32 v[126:127], v[126:127], v[128:129] op_sel_hi:[1,0]
	v_mov_b32_e32 v148, v121
	v_add_f32_e32 v123, 1.0, v123
	v_rcp_f32_e32 v151, v123
	v_mul_f32_e32 v123, 0xbfb8aa3b, v124
	v_exp_f32_e32 v123, v123
	v_pk_mul_f32 v[118:119], v[118:119], v[128:129] op_sel_hi:[1,0]
	v_pk_mul_f32 v[150:151], v[152:153], v[150:151]
	v_pk_mul_f32 v[116:117], v[116:117], v[128:129] op_sel_hi:[1,0]
	v_add_f32_e32 v123, 1.0, v123
	v_pk_mul_f32 v[120:121], v[148:149], v[150:151]
	v_rcp_f32_e32 v148, v123
	v_mul_f32_e32 v123, 0xbfb8aa3b, v126
	v_exp_f32_e32 v123, v123
	v_mov_b32_e32 v150, v124
	v_mov_b32_e32 v151, v126
	v_mov_b32_e32 v126, v125
	v_add_f32_e32 v123, 1.0, v123
	v_rcp_f32_e32 v149, v123
	v_ashrrev_i32_e32 v123, 31, v122
	v_lshlrev_b64 v[122:123], 1, v[122:123]
	v_pk_mul_f32 v[114:115], v[114:115], v[128:129] op_sel_hi:[1,0]
	v_pk_mul_f32 v[148:149], v[150:151], v[148:149]
	v_pk_mul_f32 v[112:113], v[112:113], v[128:129] op_sel_hi:[1,0]
	v_pk_mul_f32 v[124:125], v[126:127], v[148:149]
	v_cvt_pk_bf16_f32 v126, v120, v121
	v_mov_b64_e32 v[120:121], s[50:51]
	v_cvt_pk_bf16_f32 v127, v124, v125
	v_mad_i64_i32 v[124:125], s[16:17], v142, s4, v[120:121]
	v_lshl_add_u64 v[124:125], v[124:125], 0, v[122:123]
	global_store_dwordx2 v[124:125], v[126:127], off
	v_mul_f32_e32 v126, 0xbfb8aa3b, v116
	v_mul_f32_e32 v127, 0xbfb8aa3b, v118
	v_exp_f32_e32 v126, v126
	v_exp_f32_e32 v127, v127
	v_mov_b32_e32 v148, v116
	v_mov_b32_e32 v149, v118
	v_add_f32_e32 v126, 1.0, v126
	v_add_f32_e32 v127, 1.0, v127
	v_rcp_f32_e32 v126, v126
	v_rcp_f32_e32 v127, v127
	v_mov_b32_e32 v118, v117
	v_pk_mul_f32 v[126:127], v[148:149], v[126:127]
	s_nop 0
	v_pk_mul_f32 v[116:117], v[118:119], v[126:127]
	v_mul_f32_e32 v118, 0xbfb8aa3b, v112
	v_mul_f32_e32 v119, 0xbfb8aa3b, v114
	v_exp_f32_e32 v118, v118
	v_exp_f32_e32 v119, v119
	v_mov_b32_e32 v126, v112
	v_mov_b32_e32 v127, v114
	v_add_f32_e32 v118, 1.0, v118
	v_add_f32_e32 v119, 1.0, v119
	v_rcp_f32_e32 v118, v118
	v_rcp_f32_e32 v119, v119
	v_mov_b32_e32 v114, v113
	v_pk_mul_f32 v[118:119], v[126:127], v[118:119]
	s_nop 0
	v_pk_mul_f32 v[112:113], v[114:115], v[118:119]
	v_cvt_pk_bf16_f32 v114, v116, v117
	v_cvt_pk_bf16_f32 v115, v112, v113
	v_or_b32_e32 v112, 16, v142
	global_store_dwordx2 v[124:125], v[114:115], off offset:128
	v_ashrrev_i32_e32 v113, 31, v112
	s_waitcnt vmcnt(8)
	v_mov_b32_e32 v114, v214
	v_mov_b32_e32 v115, v215
	v_mov_b32_e32 v128, v115
	v_lshlrev_b64 v[116:117], s14, v[128:129]
	v_min_u32_e32 v113, 1, v116
	v_or_b32_e32 v113, v117, v113
	v_cvt_f32_u32_e32 v113, v113
	v_cvt_f32_u32_e32 v114, v114
	v_ldexp_f32 v113, v113, s15
	v_fmac_f32_e32 v113, 0x2f800000, v114
	v_fmamk_f32 v113, v113, 0x3a000000, v195
	v_cmp_gt_f32_e32 vcc, s27, v113
	v_mul_f32_e32 v114, 0x4b800000, v113
	s_nop 0
	v_cndmask_b32_e32 v113, v113, v114, vcc
	v_rsq_f32_e32 v113, v113
	s_nop 0
	v_mul_f32_e32 v114, 0x45800000, v113
	v_cndmask_b32_e32 v114, v113, v114, vcc
	v_pk_mul_f32 v[108:109], v[108:109], v[114:115] op_sel_hi:[1,0]
	v_pk_mul_f32 v[110:111], v[110:111], v[114:115] op_sel_hi:[1,0]
	v_mul_f32_e32 v113, 0xbfb8aa3b, v108
	v_exp_f32_e32 v113, v113
	v_mov_b32_e32 v118, v108
	v_mov_b32_e32 v119, v110
	v_pk_mul_f32 v[106:107], v[106:107], v[114:115] op_sel_hi:[1,0]
	v_add_f32_e32 v113, 1.0, v113
	v_rcp_f32_e32 v116, v113
	v_mul_f32_e32 v113, 0xbfb8aa3b, v110
	v_exp_f32_e32 v113, v113
	v_pk_mul_f32 v[104:105], v[104:105], v[114:115] op_sel_hi:[1,0]
	v_mov_b32_e32 v110, v109
	v_pk_mul_f32 v[102:103], v[102:103], v[114:115] op_sel_hi:[1,0]
	v_add_f32_e32 v113, 1.0, v113
	v_rcp_f32_e32 v117, v113
	v_pk_mul_f32 v[100:101], v[100:101], v[114:115] op_sel_hi:[1,0]
	v_pk_mul_f32 v[98:99], v[98:99], v[114:115] op_sel_hi:[1,0]
	v_pk_mul_f32 v[96:97], v[96:97], v[114:115] op_sel_hi:[1,0]
	v_pk_mul_f32 v[116:117], v[118:119], v[116:117]
	s_nop 0
	v_pk_mul_f32 v[108:109], v[110:111], v[116:117]
; DI float ss_get(const ssacc_t* p) { const ssacc_t v = *p; return (float)(unsigned)(v >> 32) + (float)(unsigned)(v & 0xffffffffull) * 2.3283064365386963e-10f; }
; DI unsigned cvtpk(float lo, float hi) { f32x2 v = {lo, hi}; bf16x2_t b = __builtin_convertvector(v, bf16x2_t); return __builtin_bit_cast(unsigned, b); }
; DI float sigmoidf_(float x) { return __builtin_amdgcn_rcpf(1.f + fexp2(-LOG2E * x)); }
;     DI void operator()(const Acc& acc, const Unit& u, int wr, int wc, int fr, int fq) const {
;     ...
;             for (int m = 0; m < 4; ++m) {
;                 asm volatile("" ::: "memory");
;                 const int row = u.pm * 256 + ai * 128 + wr * 64 + m * 16 + fr;
;                 const float rs = rsqrtf(ss_get(ssx1 + row) * (1.f / 2048.f) + EPS_);
; #pragma unroll
;                 for (int bj = 0; bj < 2; ++bj) {
;                     const f32x4 v0 = acc[ai][bj][m][0] * rs, v1 = acc[ai][bj][m][1] * rs;
;                     const int i0 = (u.pn * 256 + bj * 128 + wc * 32 + 8 * fq) >> 1;
;                     const float o0 = v0[0] * sigmoidf_(v0[0]) * v0[1], o1 = v0[2] * sigmoidf_(v0[2]) * v0[3];
;                     const float o2 = v1[0] * sigmoidf_(v1[0]) * v1[1], o3 = v1[2] * sigmoidf_(v1[2]) * v1[3];
;                     u32x2 w; w.x = cvtpk(o0, o1); w.y = cvtpk(o2, o3);
;                     *(u32x2*)(HM + (size_t)row * DFF_ + i0) = w;
;                 }
	v_mul_f32_e32 v110, 0xbfb8aa3b, v104
	v_mul_f32_e32 v111, 0xbfb8aa3b, v106
	v_exp_f32_e32 v110, v110
	v_exp_f32_e32 v111, v111
	v_mov_b32_e32 v116, v104
	v_mov_b32_e32 v117, v106
	v_add_f32_e32 v110, 1.0, v110
	v_add_f32_e32 v111, 1.0, v111
	v_rcp_f32_e32 v110, v110
	v_rcp_f32_e32 v111, v111
	v_mov_b32_e32 v106, v105
	v_pk_mul_f32 v[110:111], v[116:117], v[110:111]
	s_nop 0
	v_pk_mul_f32 v[104:105], v[106:107], v[110:111]
	v_cvt_pk_bf16_f32 v106, v108, v109
	v_cvt_pk_bf16_f32 v107, v104, v105
	v_mad_i64_i32 v[104:105], s[16:17], v112, s4, v[120:121]
	v_lshl_add_u64 v[104:105], v[104:105], 0, v[122:123]
	global_store_dwordx2 v[104:105], v[106:107], off
	v_mul_f32_e32 v106, 0xbfb8aa3b, v100
	v_mul_f32_e32 v107, 0xbfb8aa3b, v102
	v_exp_f32_e32 v106, v106
	v_exp_f32_e32 v107, v107
	v_mov_b32_e32 v108, v100
	v_mov_b32_e32 v109, v102
	v_add_f32_e32 v106, 1.0, v106
	v_add_f32_e32 v107, 1.0, v107
	v_rcp_f32_e32 v106, v106
	v_rcp_f32_e32 v107, v107
	v_mov_b32_e32 v102, v101
	v_pk_mul_f32 v[106:107], v[108:109], v[106:107]
	s_nop 0
	v_pk_mul_f32 v[100:101], v[102:103], v[106:107]
	v_mul_f32_e32 v102, 0xbfb8aa3b, v96
	v_mul_f32_e32 v103, 0xbfb8aa3b, v98
	v_exp_f32_e32 v102, v102
	v_exp_f32_e32 v103, v103
	v_mov_b32_e32 v106, v96
	v_mov_b32_e32 v107, v98
	v_add_f32_e32 v102, 1.0, v102
	v_add_f32_e32 v103, 1.0, v103
	v_rcp_f32_e32 v102, v102
	v_rcp_f32_e32 v103, v103
	v_mov_b32_e32 v98, v97
	v_pk_mul_f32 v[102:103], v[106:107], v[102:103]
	s_nop 0
	v_pk_mul_f32 v[96:97], v[98:99], v[102:103]
	v_cvt_pk_bf16_f32 v98, v100, v101
	v_cvt_pk_bf16_f32 v99, v96, v97
	v_or_b32_e32 v96, 32, v142
	global_store_dwordx2 v[104:105], v[98:99], off offset:128
	v_ashrrev_i32_e32 v97, 31, v96
	s_waitcnt vmcnt(9)
	v_mov_b32_e32 v98, v216
	v_mov_b32_e32 v99, v217
	v_mov_b32_e32 v128, v99
	v_lshlrev_b64 v[100:101], s14, v[128:129]
	v_min_u32_e32 v97, 1, v100
	v_or_b32_e32 v97, v101, v97
	v_cvt_f32_u32_e32 v97, v97
	v_cvt_f32_u32_e32 v98, v98
	v_ldexp_f32 v97, v97, s15
	v_fmac_f32_e32 v97, 0x2f800000, v98
	v_fmamk_f32 v97, v97, 0x3a000000, v195
	v_cmp_gt_f32_e32 vcc, s27, v97
	v_mul_f32_e32 v98, 0x4b800000, v97
	s_nop 0
	v_cndmask_b32_e32 v97, v97, v98, vcc
	v_rsq_f32_e32 v97, v97
	s_nop 0
	v_mul_f32_e32 v98, 0x45800000, v97
	v_cndmask_b32_e32 v98, v97, v98, vcc
	v_pk_mul_f32 v[92:93], v[92:93], v[98:99] op_sel_hi:[1,0]
	v_pk_mul_f32 v[94:95], v[94:95], v[98:99] op_sel_hi:[1,0]
	v_mul_f32_e32 v97, 0xbfb8aa3b, v92
	v_exp_f32_e32 v97, v97
	v_mov_b32_e32 v102, v92
	v_mov_b32_e32 v103, v94
	v_pk_mul_f32 v[90:91], v[90:91], v[98:99] op_sel_hi:[1,0]
	v_add_f32_e32 v97, 1.0, v97
	v_rcp_f32_e32 v100, v97
	v_mul_f32_e32 v97, 0xbfb8aa3b, v94
	v_exp_f32_e32 v97, v97
	v_pk_mul_f32 v[88:89], v[88:89], v[98:99] op_sel_hi:[1,0]
	v_mov_b32_e32 v94, v93
	v_pk_mul_f32 v[86:87], v[86:87], v[98:99] op_sel_hi:[1,0]
	v_add_f32_e32 v97, 1.0, v97
	v_rcp_f32_e32 v101, v97
	v_pk_mul_f32 v[84:85], v[84:85], v[98:99] op_sel_hi:[1,0]
	v_pk_mul_f32 v[82:83], v[82:83], v[98:99] op_sel_hi:[1,0]
	v_pk_mul_f32 v[80:81], v[80:81], v[98:99] op_sel_hi:[1,0]
	v_pk_mul_f32 v[100:101], v[102:103], v[100:101]
	s_nop 0
	v_pk_mul_f32 v[92:93], v[94:95], v[100:101]
	v_mul_f32_e32 v94, 0xbfb8aa3b, v88
	v_mul_f32_e32 v95, 0xbfb8aa3b, v90
	v_exp_f32_e32 v94, v94
	v_exp_f32_e32 v95, v95
	v_mov_b32_e32 v100, v88
	v_mov_b32_e32 v101, v90
	v_add_f32_e32 v94, 1.0, v94
	v_add_f32_e32 v95, 1.0, v95
	v_rcp_f32_e32 v94, v94
	v_rcp_f32_e32 v95, v95
	v_mov_b32_e32 v90, v89
	v_pk_mul_f32 v[94:95], v[100:101], v[94:95]
	s_nop 0
	v_pk_mul_f32 v[88:89], v[90:91], v[94:95]
	v_cvt_pk_bf16_f32 v90, v92, v93
	v_cvt_pk_bf16_f32 v91, v88, v89
	v_mad_i64_i32 v[88:89], s[16:17], v96, s4, v[120:121]
	v_lshl_add_u64 v[88:89], v[88:89], 0, v[122:123]
	global_store_dwordx2 v[88:89], v[90:91], off
	v_mul_f32_e32 v90, 0xbfb8aa3b, v84
	v_mul_f32_e32 v91, 0xbfb8aa3b, v86
	v_exp_f32_e32 v90, v90
	v_exp_f32_e32 v91, v91
	v_mov_b32_e32 v92, v84
	v_mov_b32_e32 v93, v86
	v_add_f32_e32 v90, 1.0, v90
	v_add_f32_e32 v91, 1.0, v91
	v_rcp_f32_e32 v90, v90
	v_rcp_f32_e32 v91, v91
	v_mov_b32_e32 v86, v85
	v_pk_mul_f32 v[90:91], v[92:93], v[90:91]
	s_nop 0
	v_pk_mul_f32 v[84:85], v[86:87], v[90:91]
	v_mul_f32_e32 v86, 0xbfb8aa3b, v80
	v_mul_f32_e32 v87, 0xbfb8aa3b, v82
	v_exp_f32_e32 v86, v86
	v_exp_f32_e32 v87, v87
	v_mov_b32_e32 v90, v80
	v_mov_b32_e32 v91, v82
	v_add_f32_e32 v86, 1.0, v86
	v_add_f32_e32 v87, 1.0, v87
	v_rcp_f32_e32 v86, v86
	v_rcp_f32_e32 v87, v87
	v_mov_b32_e32 v82, v81
	v_pk_mul_f32 v[86:87], v[90:91], v[86:87]
	s_nop 0
	v_pk_mul_f32 v[80:81], v[82:83], v[86:87]
	v_cvt_pk_bf16_f32 v82, v84, v85
	v_cvt_pk_bf16_f32 v83, v80, v81
	v_or_b32_e32 v80, 48, v142
	global_store_dwordx2 v[88:89], v[82:83], off offset:128
	v_ashrrev_i32_e32 v81, 31, v80
	s_waitcnt vmcnt(10)
; DI float ss_get(const ssacc_t* p) { const ssacc_t v = *p; return (float)(unsigned)(v >> 32) + (float)(unsigned)(v & 0xffffffffull) * 2.3283064365386963e-10f; }
; DI unsigned cvtpk(float lo, float hi) { f32x2 v = {lo, hi}; bf16x2_t b = __builtin_convertvector(v, bf16x2_t); return __builtin_bit_cast(unsigned, b); }
; DI float sigmoidf_(float x) { return __builtin_amdgcn_rcpf(1.f + fexp2(-LOG2E * x)); }
;     DI void operator()(const Acc& acc, const Unit& u, int wr, int wc, int fr, int fq) const {
;     ...
;             for (int m = 0; m < 4; ++m) {
;                 asm volatile("" ::: "memory");
;                 const int row = u.pm * 256 + ai * 128 + wr * 64 + m * 16 + fr;
;                 const float rs = rsqrtf(ss_get(ssx1 + row) * (1.f / 2048.f) + EPS_);
; #pragma unroll
;                 for (int bj = 0; bj < 2; ++bj) {
;                     const f32x4 v0 = acc[ai][bj][m][0] * rs, v1 = acc[ai][bj][m][1] * rs;
;                     const int i0 = (u.pn * 256 + bj * 128 + wc * 32 + 8 * fq) >> 1;
;                     const float o0 = v0[0] * sigmoidf_(v0[0]) * v0[1], o1 = v0[2] * sigmoidf_(v0[2]) * v0[3];
;                     const float o2 = v1[0] * sigmoidf_(v1[0]) * v1[1], o3 = v1[2] * sigmoidf_(v1[2]) * v1[3];
;                     u32x2 w; w.x = cvtpk(o0, o1); w.y = cvtpk(o2, o3);
;                     *(u32x2*)(HM + (size_t)row * DFF_ + i0) = w;
;                 }
	v_mov_b32_e32 v82, v218
	v_mov_b32_e32 v83, v219
	v_mov_b32_e32 v128, v83
	v_lshlrev_b64 v[84:85], s14, v[128:129]
	v_min_u32_e32 v81, 1, v84
	v_or_b32_e32 v81, v85, v81
	v_cvt_f32_u32_e32 v81, v81
	v_cvt_f32_u32_e32 v82, v82
	v_ldexp_f32 v81, v81, s15
	v_fmac_f32_e32 v81, 0x2f800000, v82
	v_fmamk_f32 v81, v81, 0x3a000000, v195
	v_cmp_gt_f32_e32 vcc, s27, v81
	v_mul_f32_e32 v82, 0x4b800000, v81
	s_nop 0
	v_cndmask_b32_e32 v81, v81, v82, vcc
	v_rsq_f32_e32 v81, v81
	s_nop 0
	v_mul_f32_e32 v82, 0x45800000, v81
	v_cndmask_b32_e32 v82, v81, v82, vcc
	v_pk_mul_f32 v[76:77], v[76:77], v[82:83] op_sel_hi:[1,0]
	v_pk_mul_f32 v[78:79], v[78:79], v[82:83] op_sel_hi:[1,0]
	v_mul_f32_e32 v81, 0xbfb8aa3b, v76
	v_exp_f32_e32 v81, v81
	v_mov_b32_e32 v86, v76
	v_mov_b32_e32 v87, v78
	v_pk_mul_f32 v[74:75], v[74:75], v[82:83] op_sel_hi:[1,0]
	v_add_f32_e32 v81, 1.0, v81
	v_rcp_f32_e32 v84, v81
	v_mul_f32_e32 v81, 0xbfb8aa3b, v78
	v_exp_f32_e32 v81, v81
	v_pk_mul_f32 v[72:73], v[72:73], v[82:83] op_sel_hi:[1,0]
	v_mov_b32_e32 v78, v77
	v_pk_mul_f32 v[70:71], v[70:71], v[82:83] op_sel_hi:[1,0]
	v_add_f32_e32 v81, 1.0, v81
	v_rcp_f32_e32 v85, v81
	v_pk_mul_f32 v[68:69], v[68:69], v[82:83] op_sel_hi:[1,0]
	v_pk_mul_f32 v[66:67], v[66:67], v[82:83] op_sel_hi:[1,0]
	v_pk_mul_f32 v[64:65], v[64:65], v[82:83] op_sel_hi:[1,0]
	v_pk_mul_f32 v[84:85], v[86:87], v[84:85]
	s_nop 0
	v_pk_mul_f32 v[76:77], v[78:79], v[84:85]
	v_mul_f32_e32 v78, 0xbfb8aa3b, v72
	v_mul_f32_e32 v79, 0xbfb8aa3b, v74
	v_exp_f32_e32 v78, v78
	v_exp_f32_e32 v79, v79
	v_mov_b32_e32 v84, v72
	v_mov_b32_e32 v85, v74
	v_add_f32_e32 v78, 1.0, v78
	v_add_f32_e32 v79, 1.0, v79
	v_rcp_f32_e32 v78, v78
	v_rcp_f32_e32 v79, v79
	v_mov_b32_e32 v74, v73
	v_pk_mul_f32 v[78:79], v[84:85], v[78:79]
	s_nop 0
	v_pk_mul_f32 v[72:73], v[74:75], v[78:79]
	v_cvt_pk_bf16_f32 v74, v76, v77
	v_cvt_pk_bf16_f32 v75, v72, v73
	v_mad_i64_i32 v[72:73], s[16:17], v80, s4, v[120:121]
	v_lshl_add_u64 v[72:73], v[72:73], 0, v[122:123]
	global_store_dwordx2 v[72:73], v[74:75], off
	v_mul_f32_e32 v74, 0xbfb8aa3b, v68
	v_mul_f32_e32 v75, 0xbfb8aa3b, v70
	v_exp_f32_e32 v74, v74
	v_exp_f32_e32 v75, v75
	v_mov_b32_e32 v76, v68
	v_mov_b32_e32 v77, v70
	v_add_f32_e32 v74, 1.0, v74
	v_add_f32_e32 v75, 1.0, v75
	v_rcp_f32_e32 v74, v74
	v_rcp_f32_e32 v75, v75
	v_mov_b32_e32 v70, v69
	v_pk_mul_f32 v[74:75], v[76:77], v[74:75]
	s_nop 0
	v_pk_mul_f32 v[68:69], v[70:71], v[74:75]
	v_mul_f32_e32 v70, 0xbfb8aa3b, v64
	v_mul_f32_e32 v71, 0xbfb8aa3b, v66
	v_exp_f32_e32 v70, v70
	v_exp_f32_e32 v71, v71
	v_mov_b32_e32 v74, v64
	v_mov_b32_e32 v75, v66
	v_add_f32_e32 v70, 1.0, v70
	v_add_f32_e32 v71, 1.0, v71
	v_rcp_f32_e32 v70, v70
	v_rcp_f32_e32 v71, v71
	v_mov_b32_e32 v66, v65
	v_pk_mul_f32 v[70:71], v[74:75], v[70:71]
	s_nop 0
	v_pk_mul_f32 v[64:65], v[66:67], v[70:71]
	v_cvt_pk_bf16_f32 v66, v68, v69
	v_cvt_pk_bf16_f32 v67, v64, v65
	v_add_u32_e32 v64, 0x80, v142
	global_store_dwordx2 v[72:73], v[66:67], off offset:128
	v_ashrrev_i32_e32 v65, 31, v64
	s_waitcnt vmcnt(11)
	v_mov_b32_e32 v66, v220
	v_mov_b32_e32 v67, v221
	v_mov_b32_e32 v128, v67
	v_lshlrev_b64 v[68:69], s14, v[128:129]
	v_min_u32_e32 v65, 1, v68
	v_or_b32_e32 v65, v69, v65
	v_cvt_f32_u32_e32 v65, v65
	v_cvt_f32_u32_e32 v66, v66
	v_ldexp_f32 v65, v65, s15
	v_fmac_f32_e32 v65, 0x2f800000, v66
	v_fmamk_f32 v65, v65, 0x3a000000, v195
	v_cmp_gt_f32_e32 vcc, s27, v65
	v_mul_f32_e32 v66, 0x4b800000, v65
	s_nop 0
	v_cndmask_b32_e32 v65, v65, v66, vcc
	v_rsq_f32_e32 v65, v65
	s_nop 0
	v_mul_f32_e32 v66, 0x45800000, v65
	v_cndmask_b32_e32 v66, v65, v66, vcc
	v_pk_mul_f32 v[60:61], v[60:61], v[66:67] op_sel_hi:[1,0]
	v_pk_mul_f32 v[62:63], v[62:63], v[66:67] op_sel_hi:[1,0]
	v_mul_f32_e32 v65, 0xbfb8aa3b, v60
	v_exp_f32_e32 v65, v65
	v_mov_b32_e32 v70, v60
	v_mov_b32_e32 v71, v62
	v_pk_mul_f32 v[58:59], v[58:59], v[66:67] op_sel_hi:[1,0]
	v_add_f32_e32 v65, 1.0, v65
	v_rcp_f32_e32 v68, v65
	v_mul_f32_e32 v65, 0xbfb8aa3b, v62
	v_exp_f32_e32 v65, v65
	v_pk_mul_f32 v[56:57], v[56:57], v[66:67] op_sel_hi:[1,0]
	v_mov_b32_e32 v62, v61
	v_pk_mul_f32 v[54:55], v[54:55], v[66:67] op_sel_hi:[1,0]
	v_add_f32_e32 v65, 1.0, v65
	v_rcp_f32_e32 v69, v65
	v_pk_mul_f32 v[52:53], v[52:53], v[66:67] op_sel_hi:[1,0]
	v_pk_mul_f32 v[50:51], v[50:51], v[66:67] op_sel_hi:[1,0]
	v_pk_mul_f32 v[48:49], v[48:49], v[66:67] op_sel_hi:[1,0]
	v_pk_mul_f32 v[68:69], v[70:71], v[68:69]
	s_nop 0
	v_pk_mul_f32 v[60:61], v[62:63], v[68:69]
	v_mul_f32_e32 v62, 0xbfb8aa3b, v56
	v_mul_f32_e32 v63, 0xbfb8aa3b, v58
	v_exp_f32_e32 v62, v62
	v_exp_f32_e32 v63, v63
	v_mov_b32_e32 v68, v56
	v_mov_b32_e32 v69, v58
	v_add_f32_e32 v62, 1.0, v62
	v_add_f32_e32 v63, 1.0, v63
	v_rcp_f32_e32 v62, v62
	v_rcp_f32_e32 v63, v63
	v_mov_b32_e32 v58, v57
	v_pk_mul_f32 v[62:63], v[68:69], v[62:63]
	s_nop 0
	v_pk_mul_f32 v[56:57], v[58:59], v[62:63]
	v_cvt_pk_bf16_f32 v58, v60, v61
	v_cvt_pk_bf16_f32 v59, v56, v57
	v_mad_i64_i32 v[56:57], s[16:17], v64, s4, v[120:121]
	v_lshl_add_u64 v[56:57], v[56:57], 0, v[122:123]
	global_store_dwordx2 v[56:57], v[58:59], off
	v_mul_f32_e32 v58, 0xbfb8aa3b, v52
	v_mul_f32_e32 v59, 0xbfb8aa3b, v54
	v_exp_f32_e32 v58, v58
	v_exp_f32_e32 v59, v59
	v_mov_b32_e32 v60, v52
	v_mov_b32_e32 v61, v54
	v_add_f32_e32 v58, 1.0, v58
	v_add_f32_e32 v59, 1.0, v59
	v_rcp_f32_e32 v58, v58
	v_rcp_f32_e32 v59, v59
	v_mov_b32_e32 v54, v53
	v_pk_mul_f32 v[58:59], v[60:61], v[58:59]
	s_nop 0
	v_pk_mul_f32 v[52:53], v[54:55], v[58:59]
	v_mul_f32_e32 v54, 0xbfb8aa3b, v48
	v_mul_f32_e32 v55, 0xbfb8aa3b, v50
	v_exp_f32_e32 v54, v54
	v_exp_f32_e32 v55, v55
	v_mov_b32_e32 v58, v48
	v_mov_b32_e32 v59, v50
	v_add_f32_e32 v54, 1.0, v54
	v_add_f32_e32 v55, 1.0, v55
	v_rcp_f32_e32 v54, v54
	v_rcp_f32_e32 v55, v55
	v_mov_b32_e32 v50, v49
	v_pk_mul_f32 v[54:55], v[58:59], v[54:55]
	s_nop 0
	v_pk_mul_f32 v[48:49], v[50:51], v[54:55]
	v_cvt_pk_bf16_f32 v50, v52, v53
	v_cvt_pk_bf16_f32 v51, v48, v49
	v_add_u32_e32 v48, 0x90, v142
	global_store_dwordx2 v[56:57], v[50:51], off offset:128
	v_ashrrev_i32_e32 v49, 31, v48
	s_waitcnt vmcnt(12)
; DI float ss_get(const ssacc_t* p) { const ssacc_t v = *p; return (float)(unsigned)(v >> 32) + (float)(unsigned)(v & 0xffffffffull) * 2.3283064365386963e-10f; }
; DI unsigned cvtpk(float lo, float hi) { f32x2 v = {lo, hi}; bf16x2_t b = __builtin_convertvector(v, bf16x2_t); return __builtin_bit_cast(unsigned, b); }
; DI float sigmoidf_(float x) { return __builtin_amdgcn_rcpf(1.f + fexp2(-LOG2E * x)); }
;     DI void operator()(const Acc& acc, const Unit& u, int wr, int wc, int fr, int fq) const {
;     ...
;             for (int m = 0; m < 4; ++m) {
;                 asm volatile("" ::: "memory");
;                 const int row = u.pm * 256 + ai * 128 + wr * 64 + m * 16 + fr;
;                 const float rs = rsqrtf(ss_get(ssx1 + row) * (1.f / 2048.f) + EPS_);
; #pragma unroll
;                 for (int bj = 0; bj < 2; ++bj) {
;                     const f32x4 v0 = acc[ai][bj][m][0] * rs, v1 = acc[ai][bj][m][1] * rs;
;                     const int i0 = (u.pn * 256 + bj * 128 + wc * 32 + 8 * fq) >> 1;
;                     const float o0 = v0[0] * sigmoidf_(v0[0]) * v0[1], o1 = v0[2] * sigmoidf_(v0[2]) * v0[3];
;                     const float o2 = v1[0] * sigmoidf_(v1[0]) * v1[1], o3 = v1[2] * sigmoidf_(v1[2]) * v1[3];
;                     u32x2 w; w.x = cvtpk(o0, o1); w.y = cvtpk(o2, o3);
;                     *(u32x2*)(HM + (size_t)row * DFF_ + i0) = w;
;                 }
	v_mov_b32_e32 v50, v222
	v_mov_b32_e32 v51, v223
	v_mov_b32_e32 v128, v51
	v_lshlrev_b64 v[52:53], s14, v[128:129]
	v_min_u32_e32 v49, 1, v52
	v_or_b32_e32 v49, v53, v49
	v_cvt_f32_u32_e32 v49, v49
	v_cvt_f32_u32_e32 v50, v50
	v_ldexp_f32 v49, v49, s15
	v_fmac_f32_e32 v49, 0x2f800000, v50
	v_fmamk_f32 v49, v49, 0x3a000000, v195
	v_cmp_gt_f32_e32 vcc, s27, v49
	v_mul_f32_e32 v50, 0x4b800000, v49
	s_nop 0
	v_cndmask_b32_e32 v49, v49, v50, vcc
	v_rsq_f32_e32 v49, v49
	s_nop 0
	v_mul_f32_e32 v50, 0x45800000, v49
	v_cndmask_b32_e32 v50, v49, v50, vcc
	v_pk_mul_f32 v[44:45], v[44:45], v[50:51] op_sel_hi:[1,0]
	v_pk_mul_f32 v[46:47], v[46:47], v[50:51] op_sel_hi:[1,0]
	v_mul_f32_e32 v49, 0xbfb8aa3b, v44
	v_exp_f32_e32 v49, v49
	v_mov_b32_e32 v54, v44
	v_mov_b32_e32 v55, v46
	v_pk_mul_f32 v[42:43], v[42:43], v[50:51] op_sel_hi:[1,0]
	v_add_f32_e32 v49, 1.0, v49
	v_rcp_f32_e32 v52, v49
	v_mul_f32_e32 v49, 0xbfb8aa3b, v46
	v_exp_f32_e32 v49, v49
	v_pk_mul_f32 v[40:41], v[40:41], v[50:51] op_sel_hi:[1,0]
	v_mov_b32_e32 v46, v45
	v_pk_mul_f32 v[38:39], v[38:39], v[50:51] op_sel_hi:[1,0]
	v_add_f32_e32 v49, 1.0, v49
	v_rcp_f32_e32 v53, v49
	v_pk_mul_f32 v[36:37], v[36:37], v[50:51] op_sel_hi:[1,0]
	v_pk_mul_f32 v[34:35], v[34:35], v[50:51] op_sel_hi:[1,0]
	v_pk_mul_f32 v[32:33], v[32:33], v[50:51] op_sel_hi:[1,0]
	v_pk_mul_f32 v[52:53], v[54:55], v[52:53]
	s_nop 0
	v_pk_mul_f32 v[44:45], v[46:47], v[52:53]
	v_mul_f32_e32 v46, 0xbfb8aa3b, v40
	v_mul_f32_e32 v47, 0xbfb8aa3b, v42
	v_exp_f32_e32 v46, v46
	v_exp_f32_e32 v47, v47
	v_mov_b32_e32 v52, v40
	v_mov_b32_e32 v53, v42
	v_add_f32_e32 v46, 1.0, v46
	v_add_f32_e32 v47, 1.0, v47
	v_rcp_f32_e32 v46, v46
	v_rcp_f32_e32 v47, v47
	v_mov_b32_e32 v42, v41
	v_pk_mul_f32 v[46:47], v[52:53], v[46:47]
	s_nop 0
	v_pk_mul_f32 v[40:41], v[42:43], v[46:47]
	v_cvt_pk_bf16_f32 v42, v44, v45
	v_cvt_pk_bf16_f32 v43, v40, v41
	v_mad_i64_i32 v[40:41], s[16:17], v48, s4, v[120:121]
	v_lshl_add_u64 v[40:41], v[40:41], 0, v[122:123]
	global_store_dwordx2 v[40:41], v[42:43], off
	v_mul_f32_e32 v42, 0xbfb8aa3b, v36
	v_mul_f32_e32 v43, 0xbfb8aa3b, v38
	v_exp_f32_e32 v42, v42
	v_exp_f32_e32 v43, v43
	v_mov_b32_e32 v44, v36
	v_mov_b32_e32 v45, v38
	v_add_f32_e32 v42, 1.0, v42
	v_add_f32_e32 v43, 1.0, v43
	v_rcp_f32_e32 v42, v42
	v_rcp_f32_e32 v43, v43
	v_mov_b32_e32 v38, v37
	v_pk_mul_f32 v[42:43], v[44:45], v[42:43]
	s_nop 0
	v_pk_mul_f32 v[36:37], v[38:39], v[42:43]
	v_mul_f32_e32 v38, 0xbfb8aa3b, v32
	v_mul_f32_e32 v39, 0xbfb8aa3b, v34
	v_exp_f32_e32 v38, v38
	v_exp_f32_e32 v39, v39
	v_mov_b32_e32 v42, v32
	v_mov_b32_e32 v43, v34
	v_add_f32_e32 v38, 1.0, v38
	v_add_f32_e32 v39, 1.0, v39
	v_rcp_f32_e32 v38, v38
	v_rcp_f32_e32 v39, v39
	v_mov_b32_e32 v34, v33
	v_pk_mul_f32 v[38:39], v[42:43], v[38:39]
	s_nop 0
	v_pk_mul_f32 v[32:33], v[34:35], v[38:39]
	v_cvt_pk_bf16_f32 v34, v36, v37
	v_cvt_pk_bf16_f32 v35, v32, v33
	v_add_u32_e32 v32, 0xa0, v142
	global_store_dwordx2 v[40:41], v[34:35], off offset:128
	v_ashrrev_i32_e32 v33, 31, v32
	s_waitcnt vmcnt(13)
; DI float ss_get(const ssacc_t* p) { const ssacc_t v = *p; return (float)(unsigned)(v >> 32) + (float)(unsigned)(v & 0xffffffffull) * 2.3283064365386963e-10f; }
; DI unsigned cvtpk(float lo, float hi) { f32x2 v = {lo, hi}; bf16x2_t b = __builtin_convertvector(v, bf16x2_t); return __builtin_bit_cast(unsigned, b); }
; DI float sigmoidf_(float x) { return __builtin_amdgcn_rcpf(1.f + fexp2(-LOG2E * x)); }
; #define PG8_BAR __builtin_amdgcn_s_barrier()
; template <class Epi, class Sched, bool ALIGN_EPI, bool SP2>
; __device__ __forceinline__ void gemm_phase(LAS unsigned char* lds, const Gemm g, const Sched& S, const Epi& E) {
;     ...
;         if constexpr (ALIGN_EPI) { if (wr == 0) PG8_BAR; }
;         E(acc, cur, wr, wc, fr, fq);
;         if (!has_next) break;
; #pragma unroll
;         for (int a = 0; a < 2; ++a)
; #pragma unroll
;             for (int b = 0; b < 2; ++b)
; #pragma unroll
;                 for (int m = 0; m < 4; ++m)
; #pragma unroll
;                     for (int n = 0; n < 2; ++n) acc[a][b][m][n] = (f32x4){0.f, 0.f, 0.f, 0.f};
;         cur = nxt; cA = nA; cB = nB; ++ui;
;         if constexpr (ALIGN_EPI) { if (wr == 1) PG8_BAR; }
;     }
;     DI void operator()(const Acc& acc, const Unit& u, int wr, int wc, int fr, int fq) const {
;     ...
;             for (int m = 0; m < 4; ++m) {
;                 asm volatile("" ::: "memory");
;                 const int row = u.pm * 256 + ai * 128 + wr * 64 + m * 16 + fr;
;                 const float rs = rsqrtf(ss_get(ssx1 + row) * (1.f / 2048.f) + EPS_);
; #pragma unroll
;                 for (int bj = 0; bj < 2; ++bj) {
;                     const f32x4 v0 = acc[ai][bj][m][0] * rs, v1 = acc[ai][bj][m][1] * rs;
;                     const int i0 = (u.pn * 256 + bj * 128 + wc * 32 + 8 * fq) >> 1;
;                     const float o0 = v0[0] * sigmoidf_(v0[0]) * v0[1], o1 = v0[2] * sigmoidf_(v0[2]) * v0[3];
;                     const float o2 = v1[0] * sigmoidf_(v1[0]) * v1[1], o3 = v1[2] * sigmoidf_(v1[2]) * v1[3];
;                     u32x2 w; w.x = cvtpk(o0, o1); w.y = cvtpk(o2, o3);
;                     *(u32x2*)(HM + (size_t)row * DFF_ + i0) = w;
;                 }
	v_mov_b32_e32 v34, v224
	v_mov_b32_e32 v35, v225
	v_mov_b32_e32 v128, v35
	v_lshlrev_b64 v[36:37], s14, v[128:129]
	v_min_u32_e32 v33, 1, v36
	v_or_b32_e32 v33, v37, v33
	v_cvt_f32_u32_e32 v33, v33
	v_cvt_f32_u32_e32 v34, v34
	v_ldexp_f32 v33, v33, s15
	v_fmac_f32_e32 v33, 0x2f800000, v34
	v_fmamk_f32 v33, v33, 0x3a000000, v195
	v_cmp_gt_f32_e32 vcc, s27, v33
	v_mul_f32_e32 v34, 0x4b800000, v33
	s_nop 0
	v_cndmask_b32_e32 v33, v33, v34, vcc
	v_rsq_f32_e32 v33, v33
	s_nop 0
	v_mul_f32_e32 v34, 0x45800000, v33
	v_cndmask_b32_e32 v34, v33, v34, vcc
	v_pk_mul_f32 v[28:29], v[28:29], v[34:35] op_sel_hi:[1,0]
	v_pk_mul_f32 v[30:31], v[30:31], v[34:35] op_sel_hi:[1,0]
	v_mul_f32_e32 v33, 0xbfb8aa3b, v28
	v_exp_f32_e32 v33, v33
	v_mov_b32_e32 v38, v28
	v_mov_b32_e32 v39, v30
	v_pk_mul_f32 v[26:27], v[26:27], v[34:35] op_sel_hi:[1,0]
	v_add_f32_e32 v33, 1.0, v33
	v_rcp_f32_e32 v36, v33
	v_mul_f32_e32 v33, 0xbfb8aa3b, v30
	v_exp_f32_e32 v33, v33
	v_pk_mul_f32 v[24:25], v[24:25], v[34:35] op_sel_hi:[1,0]
	v_mov_b32_e32 v30, v29
	v_pk_mul_f32 v[22:23], v[22:23], v[34:35] op_sel_hi:[1,0]
	v_add_f32_e32 v33, 1.0, v33
	v_rcp_f32_e32 v37, v33
	v_pk_mul_f32 v[20:21], v[20:21], v[34:35] op_sel_hi:[1,0]
	v_pk_mul_f32 v[18:19], v[18:19], v[34:35] op_sel_hi:[1,0]
	v_pk_mul_f32 v[16:17], v[16:17], v[34:35] op_sel_hi:[1,0]
	v_pk_mul_f32 v[36:37], v[38:39], v[36:37]
	s_nop 0
	v_pk_mul_f32 v[28:29], v[30:31], v[36:37]
	v_mul_f32_e32 v30, 0xbfb8aa3b, v24
	v_mul_f32_e32 v31, 0xbfb8aa3b, v26
	v_exp_f32_e32 v30, v30
	v_exp_f32_e32 v31, v31
	v_mov_b32_e32 v36, v24
	v_mov_b32_e32 v37, v26
	v_add_f32_e32 v30, 1.0, v30
	v_add_f32_e32 v31, 1.0, v31
	v_rcp_f32_e32 v30, v30
	v_rcp_f32_e32 v31, v31
	v_mov_b32_e32 v26, v25
	v_pk_mul_f32 v[30:31], v[36:37], v[30:31]
	s_nop 0
	v_pk_mul_f32 v[24:25], v[26:27], v[30:31]
	v_cvt_pk_bf16_f32 v26, v28, v29
	v_cvt_pk_bf16_f32 v27, v24, v25
	v_mad_i64_i32 v[24:25], s[16:17], v32, s4, v[120:121]
	v_lshl_add_u64 v[24:25], v[24:25], 0, v[122:123]
	global_store_dwordx2 v[24:25], v[26:27], off
	v_mul_f32_e32 v26, 0xbfb8aa3b, v20
	v_mul_f32_e32 v27, 0xbfb8aa3b, v22
	v_exp_f32_e32 v26, v26
	v_exp_f32_e32 v27, v27
	v_mov_b32_e32 v28, v20
	v_mov_b32_e32 v29, v22
	v_add_f32_e32 v26, 1.0, v26
	v_add_f32_e32 v27, 1.0, v27
	v_rcp_f32_e32 v26, v26
	v_rcp_f32_e32 v27, v27
	v_mov_b32_e32 v22, v21
	v_pk_mul_f32 v[26:27], v[28:29], v[26:27]
	s_nop 0
	v_pk_mul_f32 v[20:21], v[22:23], v[26:27]
	v_mul_f32_e32 v22, 0xbfb8aa3b, v16
	v_mul_f32_e32 v23, 0xbfb8aa3b, v18
	v_exp_f32_e32 v22, v22
	v_exp_f32_e32 v23, v23
	v_mov_b32_e32 v26, v16
	v_mov_b32_e32 v27, v18
	v_add_f32_e32 v22, 1.0, v22
	v_add_f32_e32 v23, 1.0, v23
	v_rcp_f32_e32 v22, v22
	v_rcp_f32_e32 v23, v23
	v_mov_b32_e32 v18, v17
	v_pk_mul_f32 v[22:23], v[26:27], v[22:23]
	s_nop 0
	v_pk_mul_f32 v[16:17], v[18:19], v[22:23]
	v_cvt_pk_bf16_f32 v18, v20, v21
	v_cvt_pk_bf16_f32 v19, v16, v17
	v_add_u32_e32 v16, 0xb0, v142
	global_store_dwordx2 v[24:25], v[18:19], off offset:128
	v_ashrrev_i32_e32 v17, 31, v16
	s_waitcnt vmcnt(14)
	v_mov_b32_e32 v18, v226
	v_mov_b32_e32 v19, v227
	v_mov_b32_e32 v128, v19
	v_lshlrev_b64 v[20:21], s14, v[128:129]
	v_min_u32_e32 v17, 1, v20
	v_or_b32_e32 v17, v21, v17
	v_cvt_f32_u32_e32 v17, v17
	v_cvt_f32_u32_e32 v18, v18
	v_ldexp_f32 v17, v17, s15
	v_fmac_f32_e32 v17, 0x2f800000, v18
	v_fmamk_f32 v17, v17, 0x3a000000, v195
	v_cmp_gt_f32_e32 vcc, s27, v17
	v_mul_f32_e32 v18, 0x4b800000, v17
	s_nop 0
	v_cndmask_b32_e32 v17, v17, v18, vcc
	v_rsq_f32_e32 v17, v17
	s_nop 0
	v_mul_f32_e32 v18, 0x45800000, v17
	v_cndmask_b32_e32 v18, v17, v18, vcc
	v_pk_mul_f32 v[12:13], v[12:13], v[18:19] op_sel_hi:[1,0]
	v_pk_mul_f32 v[14:15], v[14:15], v[18:19] op_sel_hi:[1,0]
	v_mul_f32_e32 v17, 0xbfb8aa3b, v12
	v_exp_f32_e32 v17, v17
	v_mov_b32_e32 v22, v12
	v_mov_b32_e32 v23, v14
	v_pk_mul_f32 v[10:11], v[10:11], v[18:19] op_sel_hi:[1,0]
	v_add_f32_e32 v17, 1.0, v17
	v_rcp_f32_e32 v20, v17
	v_mul_f32_e32 v17, 0xbfb8aa3b, v14
	v_exp_f32_e32 v17, v17
	v_pk_mul_f32 v[8:9], v[8:9], v[18:19] op_sel_hi:[1,0]
	v_mov_b32_e32 v14, v13
	v_pk_mul_f32 v[6:7], v[6:7], v[18:19] op_sel_hi:[1,0]
	v_add_f32_e32 v17, 1.0, v17
	v_rcp_f32_e32 v21, v17
	v_pk_mul_f32 v[4:5], v[4:5], v[18:19] op_sel_hi:[1,0]
	v_pk_mul_f32 v[2:3], v[2:3], v[18:19] op_sel_hi:[1,0]
	v_pk_mul_f32 v[0:1], v[0:1], v[18:19] op_sel_hi:[1,0]
	v_pk_mul_f32 v[20:21], v[22:23], v[20:21]
	s_and_b64 vcc, exec, s[48:49]
	v_pk_mul_f32 v[12:13], v[14:15], v[20:21]
	v_mul_f32_e32 v14, 0xbfb8aa3b, v8
	v_mul_f32_e32 v15, 0xbfb8aa3b, v10
	v_exp_f32_e32 v14, v14
	v_exp_f32_e32 v15, v15
	v_mov_b32_e32 v20, v8
	v_mov_b32_e32 v21, v10
	v_add_f32_e32 v14, 1.0, v14
	v_add_f32_e32 v15, 1.0, v15
	v_rcp_f32_e32 v14, v14
	v_rcp_f32_e32 v15, v15
	v_mov_b32_e32 v10, v9
	v_pk_mul_f32 v[14:15], v[20:21], v[14:15]
	s_nop 0
	v_pk_mul_f32 v[8:9], v[10:11], v[14:15]
	v_cvt_pk_bf16_f32 v10, v12, v13
	v_cvt_pk_bf16_f32 v11, v8, v9
	v_mad_i64_i32 v[8:9], s[14:15], v16, s4, v[120:121]
	v_lshl_add_u64 v[8:9], v[8:9], 0, v[122:123]
	global_store_dwordx2 v[8:9], v[10:11], off
	v_mul_f32_e32 v10, 0xbfb8aa3b, v4
	v_mul_f32_e32 v11, 0xbfb8aa3b, v6
	v_exp_f32_e32 v10, v10
	v_exp_f32_e32 v11, v11
	v_mov_b32_e32 v12, v4
	v_mov_b32_e32 v13, v6
	v_add_f32_e32 v10, 1.0, v10
	v_add_f32_e32 v11, 1.0, v11
	v_rcp_f32_e32 v10, v10
	v_rcp_f32_e32 v11, v11
	v_mov_b32_e32 v6, v5
	s_mov_b64 s[14:15], -1
	v_pk_mul_f32 v[10:11], v[12:13], v[10:11]
	s_nop 0
	v_pk_mul_f32 v[4:5], v[6:7], v[10:11]
	v_mul_f32_e32 v6, 0xbfb8aa3b, v0
	v_mul_f32_e32 v7, 0xbfb8aa3b, v2
	v_exp_f32_e32 v6, v6
	v_exp_f32_e32 v7, v7
	v_mov_b32_e32 v10, v0
	v_mov_b32_e32 v11, v2
	v_add_f32_e32 v6, 1.0, v6
	v_add_f32_e32 v7, 1.0, v7
	v_rcp_f32_e32 v6, v6
	v_rcp_f32_e32 v7, v7
	v_mov_b32_e32 v2, v1
	v_pk_mul_f32 v[6:7], v[10:11], v[6:7]
	s_nop 0
	v_pk_mul_f32 v[0:1], v[2:3], v[6:7]
	v_cvt_pk_bf16_f32 v2, v4, v5
	v_cvt_pk_bf16_f32 v3, v0, v1
	global_store_dwordx2 v[8:9], v[2:3], off offset:128
	s_cbranch_vccnz .LBB0_1356
	s_andn2_b64 vcc, exec, s[42:43]
	s_cbranch_vccnz .LBB0_1355
	s_barrier
	s_branch .LBB0_1355
